# merge/out K-loops: M0 computed by SALU from one readfirstlane base plus constants, scalar-base LDS-DMA (no readfirstlane or v_lshl_add_u64 in those K-loops)
# speedup vs baseline: 1.0201x; 1.0048x over previous
.LBB0_829:
	v_and_b32_e32 v2, 15, v1
	v_and_b32_e32 v3, 48, v1
	v_lshlrev_b32_e32 v2, 6, v2
	v_lshlrev_b32_e32 v1, 2, v1
	v_or_b32_e32 v4, v2, v3
	v_and_b32_e32 v1, 32, v1
	s_lshl_b32 s38, s38, 13
	v_bitop3_b32 v4, v4, s38, v1 bitop3:0xde
	s_lshl_b32 s38, s47, 6
	v_bitop3_b32 v2, v2, v1, v3 bitop3:0x36
	s_and_b32 s38, s38, 0x3000
	v_or_b32_e32 v136, s38, v2
	s_add_u32 s38, s0, 0x80
	s_addc_u32 s39, s1, 0
	v_add_u32_e32 v137, s93, v0
	v_lshl_add_u64 v[2:3], s[38:39], 0, v[192:193]
	v_readfirstlane_b32 s38, v137
	v_add_u32_e32 v138, 0x2000, v137
	s_mov_b32 m0, s38
	v_readfirstlane_b32 s38, v138
	s_waitcnt vmcnt(4)
	s_barrier
	global_load_lds_dwordx4 v[2:3], off
	s_mov_b32 m0, s38
	s_add_u32 s38, s2, 0x80
	v_lshl_add_u64 v[2:3], v[2:3], 0, s[6:7]
	s_addc_u32 s39, s3, 0
	v_add_u32_e32 v139, 0x8000, v130
	global_load_lds_dwordx4 v[2:3], off
	v_lshl_add_u64 v[2:3], s[38:39], 0, v[192:193]
	v_readfirstlane_b32 s38, v139
	v_add_u32_e32 v140, 0xa000, v130
	s_mov_b32 m0, s38
	v_readfirstlane_b32 s38, v140
	global_load_lds_dwordx4 v[2:3], off
	s_mov_b32 m0, s38
	s_add_u32 s38, s36, 0x80
	v_lshl_add_u64 v[2:3], v[2:3], 0, s[6:7]
	s_addc_u32 s39, s37, 0
	v_add_u32_e32 v141, s89, v0
	global_load_lds_dwordx4 v[2:3], off
	v_lshl_add_u64 v[2:3], s[38:39], 0, v[192:193]
	v_readfirstlane_b32 s38, v141
	v_add_u32_e32 v142, 0x2000, v141
	s_mov_b32 m0, s38
	v_readfirstlane_b32 s38, v142
	global_load_lds_dwordx4 v[2:3], off
	v_lshl_add_u64 v[0:1], v[2:3], 0, s[6:7]
	s_mov_b32 m0, s38
	s_mov_b32 s52, -2
	global_load_lds_dwordx4 v[0:1], off
	s_waitcnt vmcnt(6)
	v_mov_b32_e32 v0, 0
	s_mov_b64 s[38:39], 0
	v_add_u32_e32 v148, 0, v4
	v_mov_b32_e32 v1, v0
	v_mov_b32_e32 v2, v0
	v_mov_b32_e32 v3, v0
	v_mov_b32_e32 v4, v0
	v_mov_b32_e32 v5, v0
	v_mov_b32_e32 v6, v0
	v_mov_b32_e32 v7, v0
	v_mov_b32_e32 v8, v0
	v_mov_b32_e32 v9, v0
	v_mov_b32_e32 v10, v0
	v_mov_b32_e32 v11, v0
	v_mov_b32_e32 v12, v0
	v_mov_b32_e32 v13, v0
	v_mov_b32_e32 v14, v0
	v_mov_b32_e32 v15, v0
	v_mov_b32_e32 v16, v0
	v_mov_b32_e32 v17, v0
	v_mov_b32_e32 v18, v0
	v_mov_b32_e32 v19, v0
	v_mov_b32_e32 v20, v0
	v_mov_b32_e32 v21, v0
	v_mov_b32_e32 v22, v0
	v_mov_b32_e32 v23, v0
	v_mov_b32_e32 v24, v0
	v_mov_b32_e32 v25, v0
	v_mov_b32_e32 v26, v0
	v_mov_b32_e32 v27, v0
	v_mov_b32_e32 v28, v0
	v_mov_b32_e32 v29, v0
	v_mov_b32_e32 v30, v0
	v_mov_b32_e32 v31, v0
	v_mov_b32_e32 v32, v0
	v_mov_b32_e32 v33, v0
	v_mov_b32_e32 v34, v0
	v_mov_b32_e32 v35, v0
	v_mov_b32_e32 v36, v0
	v_mov_b32_e32 v37, v0
	v_mov_b32_e32 v38, v0
	v_mov_b32_e32 v39, v0
	v_mov_b32_e32 v40, v0
	v_mov_b32_e32 v41, v0
	v_mov_b32_e32 v42, v0
	v_mov_b32_e32 v43, v0
	v_mov_b32_e32 v44, v0
	v_mov_b32_e32 v45, v0
	v_mov_b32_e32 v46, v0
	v_mov_b32_e32 v47, v0
	v_mov_b32_e32 v48, v0
	v_mov_b32_e32 v49, v0
	v_mov_b32_e32 v50, v0
	v_mov_b32_e32 v51, v0
	v_mov_b32_e32 v52, v0
	v_mov_b32_e32 v53, v0
	v_mov_b32_e32 v54, v0
	v_mov_b32_e32 v55, v0
	v_mov_b32_e32 v56, v0
	v_mov_b32_e32 v57, v0
	v_mov_b32_e32 v58, v0
	v_mov_b32_e32 v59, v0
	v_mov_b32_e32 v60, v0
	v_mov_b32_e32 v61, v0
	v_mov_b32_e32 v62, v0
	v_mov_b32_e32 v63, v0
	v_mov_b32_e32 v64, v0
	v_mov_b32_e32 v65, v0
	v_mov_b32_e32 v66, v0
	v_mov_b32_e32 v67, v0
	v_mov_b32_e32 v68, v0
	v_mov_b32_e32 v69, v0
	v_mov_b32_e32 v70, v0
	v_mov_b32_e32 v71, v0
	v_mov_b32_e32 v72, v0
	v_mov_b32_e32 v73, v0
	v_mov_b32_e32 v74, v0
	v_mov_b32_e32 v75, v0
	v_mov_b32_e32 v76, v0
	v_mov_b32_e32 v77, v0
	v_mov_b32_e32 v78, v0
	v_mov_b32_e32 v79, v0
	v_mov_b32_e32 v80, v0
	v_mov_b32_e32 v81, v0
	v_mov_b32_e32 v82, v0
	v_mov_b32_e32 v83, v0
	v_mov_b32_e32 v84, v0
	v_mov_b32_e32 v85, v0
	v_mov_b32_e32 v86, v0
	v_mov_b32_e32 v87, v0
	v_mov_b32_e32 v88, v0
	v_mov_b32_e32 v89, v0
	v_mov_b32_e32 v90, v0
	v_mov_b32_e32 v91, v0
	v_mov_b32_e32 v92, v0
	v_mov_b32_e32 v93, v0
	v_mov_b32_e32 v94, v0
	v_mov_b32_e32 v95, v0
	v_mov_b32_e32 v96, v0
	v_mov_b32_e32 v97, v0
	v_mov_b32_e32 v98, v0
	v_mov_b32_e32 v99, v0
	v_mov_b32_e32 v100, v0
	v_mov_b32_e32 v101, v0
	v_mov_b32_e32 v102, v0
	v_mov_b32_e32 v103, v0
	v_mov_b32_e32 v104, v0
	v_mov_b32_e32 v105, v0
	v_mov_b32_e32 v106, v0
	v_mov_b32_e32 v107, v0
	v_mov_b32_e32 v108, v0
	v_mov_b32_e32 v109, v0
	v_mov_b32_e32 v110, v0
	v_mov_b32_e32 v111, v0
	v_mov_b32_e32 v112, v0
	v_mov_b32_e32 v113, v0
	v_mov_b32_e32 v114, v0
	v_mov_b32_e32 v115, v0
	v_mov_b32_e32 v116, v0
	v_mov_b32_e32 v117, v0
	v_mov_b32_e32 v118, v0
	v_mov_b32_e32 v119, v0
	v_mov_b32_e32 v120, v0
	v_mov_b32_e32 v121, v0
	v_mov_b32_e32 v122, v0
	v_mov_b32_e32 v123, v0
	v_mov_b32_e32 v124, v0
	v_mov_b32_e32 v125, v0
	v_mov_b32_e32 v126, v0
	v_mov_b32_e32 v127, v0
	v_readfirstlane_b32 s9, v130
	s_barrier
.LBB0_830:
	v_add_u32_e32 v143, s77, v136
	ds_read_b128 v[150:153], v143
	ds_read_b128 v[154:157], v143 offset:1024
	ds_read_b128 v[158:161], v143 offset:2048
	ds_read_b128 v[162:165], v143 offset:3072
	s_add_u32 s53, s12, s38
	s_addc_u32 s72, s13, s39
	s_add_u32 s54, s53, 0x80
	s_addc_u32 s55, s72, 0
	v_add_u32_e32 v143, 0xc000, v130
	s_add_i32 m0, s9, 0xc000
	ds_read_b128 v[166:169], v148
	ds_read_b128 v[170:173], v148 offset:1024
	ds_read_b128 v[174:177], v148 offset:2048
	ds_read_b128 v[178:181], v148 offset:3072
	ds_read_b128 v[182:185], v148 offset:4096
	ds_read_b128 v[186:189], v148 offset:5120
	ds_read_b128 v[196:199], v148 offset:6144
	ds_read_b128 v[200:203], v148 offset:7168
	global_load_lds_dwordx4 v192, s[54:55]
	s_add_u32 s14, s54, s6
	s_addc_u32 s15, s55, s7
	v_add_u32_e32 v144, 0xe000, v130
	s_nop 0
	s_add_i32 m0, s9, 0xe000
	s_nop 0
	global_load_lds_dwordx4 v192, s[14:15]
	s_waitcnt lgkmcnt(8)
	s_barrier
	s_waitcnt lgkmcnt(0)
	s_waitcnt lgkmcnt(0)
	v_mfma_f32_16x16x32_bf16 v[124:127], v[166:169], v[150:153], v[124:127]
	v_mfma_f32_16x16x32_bf16 v[120:123], v[166:169], v[158:161], v[120:123]
	v_mfma_f32_16x16x32_bf16 v[116:119], v[174:177], v[150:153], v[116:119]
	v_mfma_f32_16x16x32_bf16 v[112:115], v[174:177], v[158:161], v[112:115]
	v_mfma_f32_16x16x32_bf16 v[108:111], v[182:185], v[150:153], v[108:111]
	v_mfma_f32_16x16x32_bf16 v[104:107], v[182:185], v[158:161], v[104:107]
	v_mfma_f32_16x16x32_bf16 v[100:103], v[196:199], v[150:153], v[100:103]
	v_mfma_f32_16x16x32_bf16 v[96:99], v[196:199], v[158:161], v[96:99]
	v_mfma_f32_16x16x32_bf16 v[124:127], v[170:173], v[154:157], v[124:127]
	v_mfma_f32_16x16x32_bf16 v[120:123], v[170:173], v[162:165], v[120:123]
	v_mfma_f32_16x16x32_bf16 v[116:119], v[178:181], v[154:157], v[116:119]
	v_mfma_f32_16x16x32_bf16 v[112:115], v[178:181], v[162:165], v[112:115]
	v_mfma_f32_16x16x32_bf16 v[108:111], v[186:189], v[154:157], v[108:111]
	v_mfma_f32_16x16x32_bf16 v[104:107], v[186:189], v[162:165], v[104:107]
	v_mfma_f32_16x16x32_bf16 v[100:103], v[200:203], v[154:157], v[100:103]
	v_mfma_f32_16x16x32_bf16 v[96:99], v[200:203], v[162:165], v[96:99]
	s_barrier
	s_add_u32 s73, s0, s38
	s_addc_u32 s74, s1, s39
	s_add_u32 s54, s73, 0x100
	s_addc_u32 s55, s74, 0
	v_add_u32_e32 v145, s33, v136
	s_add_i32 m0, s9, s77
	ds_read_b128 v[204:207], v145
	ds_read_b128 v[208:211], v145 offset:1024
	ds_read_b128 v[212:215], v145 offset:2048
	ds_read_b128 v[216:219], v145 offset:3072
	global_load_lds_dwordx4 v192, s[54:55]
	s_add_u32 s14, s54, s6
	s_addc_u32 s15, s55, s7
	s_add_i32 m0, s9, s77
	s_add_i32 m0, m0, 0x2000
	s_nop 0
	global_load_lds_dwordx4 v192, s[14:15]
	s_barrier
	s_waitcnt lgkmcnt(0)
	s_waitcnt lgkmcnt(0)
	v_mfma_f32_16x16x32_bf16 v[92:95], v[166:169], v[204:207], v[92:95]
	v_mfma_f32_16x16x32_bf16 v[88:91], v[166:169], v[212:215], v[88:91]
	v_mfma_f32_16x16x32_bf16 v[84:87], v[174:177], v[204:207], v[84:87]
	v_mfma_f32_16x16x32_bf16 v[80:83], v[174:177], v[212:215], v[80:83]
	v_mfma_f32_16x16x32_bf16 v[76:79], v[182:185], v[204:207], v[76:79]
	v_mfma_f32_16x16x32_bf16 v[72:75], v[182:185], v[212:215], v[72:75]
	v_mfma_f32_16x16x32_bf16 v[68:71], v[196:199], v[204:207], v[68:71]
	v_mfma_f32_16x16x32_bf16 v[64:67], v[196:199], v[212:215], v[64:67]
	v_mfma_f32_16x16x32_bf16 v[92:95], v[170:173], v[208:211], v[92:95]
	v_mfma_f32_16x16x32_bf16 v[88:91], v[170:173], v[216:219], v[88:91]
	v_mfma_f32_16x16x32_bf16 v[84:87], v[178:181], v[208:211], v[84:87]
	v_mfma_f32_16x16x32_bf16 v[80:83], v[178:181], v[216:219], v[80:83]
	v_mfma_f32_16x16x32_bf16 v[76:79], v[186:189], v[208:211], v[76:79]
	v_mfma_f32_16x16x32_bf16 v[72:75], v[186:189], v[216:219], v[72:75]
	v_mfma_f32_16x16x32_bf16 v[68:71], v[200:203], v[208:211], v[68:71]
	v_mfma_f32_16x16x32_bf16 v[64:67], v[200:203], v[216:219], v[64:67]
	s_add_u32 s75, s2, s38
	s_addc_u32 s78, s3, s39
	s_add_u32 s54, s75, 0x100
	s_addc_u32 s55, s78, 0
	s_mov_b32 m0, s9
	s_barrier
	ds_read_b128 v[166:169], v148 offset:16384
	ds_read_b128 v[170:173], v148 offset:17408
	ds_read_b128 v[174:177], v148 offset:18432
	ds_read_b128 v[178:181], v148 offset:19456
	ds_read_b128 v[182:185], v148 offset:20480
	ds_read_b128 v[186:189], v148 offset:21504
	ds_read_b128 v[196:199], v148 offset:22528
	ds_read_b128 v[200:203], v148 offset:23552
	global_load_lds_dwordx4 v192, s[54:55]
	s_add_u32 s14, s54, s6
	s_addc_u32 s15, s55, s7
	s_add_i32 m0, s9, 0x2000
	s_nop 0
	global_load_lds_dwordx4 v192, s[14:15]
	s_barrier
	s_waitcnt lgkmcnt(0)
	s_waitcnt lgkmcnt(0)
	v_mfma_f32_16x16x32_bf16 v[60:63], v[166:169], v[150:153], v[60:63]
	v_mfma_f32_16x16x32_bf16 v[56:59], v[166:169], v[158:161], v[56:59]
	v_mfma_f32_16x16x32_bf16 v[52:55], v[174:177], v[150:153], v[52:55]
	v_mfma_f32_16x16x32_bf16 v[48:51], v[174:177], v[158:161], v[48:51]
	v_mfma_f32_16x16x32_bf16 v[44:47], v[182:185], v[150:153], v[44:47]
	v_mfma_f32_16x16x32_bf16 v[40:43], v[182:185], v[158:161], v[40:43]
	v_mfma_f32_16x16x32_bf16 v[36:39], v[196:199], v[150:153], v[36:39]
	v_mfma_f32_16x16x32_bf16 v[32:35], v[196:199], v[158:161], v[32:35]
	v_mfma_f32_16x16x32_bf16 v[60:63], v[170:173], v[154:157], v[60:63]
	v_mfma_f32_16x16x32_bf16 v[56:59], v[170:173], v[162:165], v[56:59]
	v_mfma_f32_16x16x32_bf16 v[52:55], v[178:181], v[154:157], v[52:55]
	v_mfma_f32_16x16x32_bf16 v[48:51], v[178:181], v[162:165], v[48:51]
	v_mfma_f32_16x16x32_bf16 v[44:47], v[186:189], v[154:157], v[44:47]
	v_mfma_f32_16x16x32_bf16 v[40:43], v[186:189], v[162:165], v[40:43]
	v_mfma_f32_16x16x32_bf16 v[36:39], v[200:203], v[154:157], v[36:39]
	v_mfma_f32_16x16x32_bf16 v[32:35], v[200:203], v[162:165], v[32:35]
	s_barrier
	s_add_u32 s79, s36, s38
	s_addc_u32 s80, s37, s39
	s_add_u32 s54, s79, 0x100
	s_addc_u32 s55, s80, 0
	s_add_i32 m0, s9, s33
	s_nop 0
	global_load_lds_dwordx4 v192, s[54:55]
	s_add_u32 s14, s54, s6
	s_addc_u32 s15, s55, s7
	s_add_i32 m0, s9, s33
	s_add_i32 m0, m0, 0x2000
	s_nop 0
	global_load_lds_dwordx4 v192, s[14:15]
	s_waitcnt vmcnt(6)
	s_barrier
	v_mfma_f32_16x16x32_bf16 v[28:31], v[166:169], v[204:207], v[28:31]
	v_mfma_f32_16x16x32_bf16 v[24:27], v[166:169], v[212:215], v[24:27]
	v_mfma_f32_16x16x32_bf16 v[20:23], v[174:177], v[204:207], v[20:23]
	v_mfma_f32_16x16x32_bf16 v[16:19], v[174:177], v[212:215], v[16:19]
	v_mfma_f32_16x16x32_bf16 v[12:15], v[182:185], v[204:207], v[12:15]
	v_mfma_f32_16x16x32_bf16 v[8:11], v[182:185], v[212:215], v[8:11]
	v_mfma_f32_16x16x32_bf16 v[4:7], v[196:199], v[204:207], v[4:7]
	v_mfma_f32_16x16x32_bf16 v[0:3], v[196:199], v[212:215], v[0:3]
	v_mfma_f32_16x16x32_bf16 v[28:31], v[170:173], v[208:211], v[28:31]
	v_mfma_f32_16x16x32_bf16 v[24:27], v[170:173], v[216:219], v[24:27]
	v_mfma_f32_16x16x32_bf16 v[20:23], v[178:181], v[208:211], v[20:23]
	v_mfma_f32_16x16x32_bf16 v[16:19], v[178:181], v[216:219], v[16:19]
	v_mfma_f32_16x16x32_bf16 v[12:15], v[186:189], v[208:211], v[12:15]
	v_mfma_f32_16x16x32_bf16 v[8:11], v[186:189], v[216:219], v[8:11]
	v_mfma_f32_16x16x32_bf16 v[4:7], v[200:203], v[208:211], v[4:7]
	v_mfma_f32_16x16x32_bf16 v[0:3], v[200:203], v[216:219], v[0:3]
	v_add_u32_e32 v145, s93, v136
	s_barrier
	ds_read_b128 v[150:153], v145
	ds_read_b128 v[154:157], v145 offset:1024
	ds_read_b128 v[158:161], v145 offset:2048
	ds_read_b128 v[162:165], v145 offset:3072
	s_add_u32 s54, s53, 0x100
	s_addc_u32 s55, s72, 0
	s_add_i32 m0, s9, 0x4000
	ds_read_b128 v[166:169], v148 offset:32768
	ds_read_b128 v[170:173], v148 offset:33792
	ds_read_b128 v[174:177], v148 offset:34816
	ds_read_b128 v[178:181], v148 offset:35840
	ds_read_b128 v[182:185], v148 offset:36864
	ds_read_b128 v[186:189], v148 offset:37888
	ds_read_b128 v[196:199], v148 offset:38912
	ds_read_b128 v[200:203], v148 offset:39936
	global_load_lds_dwordx4 v192, s[54:55]
	s_add_u32 s14, s54, s6
	s_addc_u32 s15, s55, s7
	s_add_i32 m0, s9, 0x6000
	s_nop 0
	global_load_lds_dwordx4 v192, s[14:15]
	s_waitcnt lgkmcnt(8)
	s_barrier
	s_waitcnt lgkmcnt(0)
	s_waitcnt lgkmcnt(0)
	v_mfma_f32_16x16x32_bf16 v[124:127], v[166:169], v[150:153], v[124:127]
	v_mfma_f32_16x16x32_bf16 v[120:123], v[166:169], v[158:161], v[120:123]
	v_mfma_f32_16x16x32_bf16 v[116:119], v[174:177], v[150:153], v[116:119]
	v_mfma_f32_16x16x32_bf16 v[112:115], v[174:177], v[158:161], v[112:115]
	v_mfma_f32_16x16x32_bf16 v[108:111], v[182:185], v[150:153], v[108:111]
	v_mfma_f32_16x16x32_bf16 v[104:107], v[182:185], v[158:161], v[104:107]
	v_mfma_f32_16x16x32_bf16 v[100:103], v[196:199], v[150:153], v[100:103]
	v_mfma_f32_16x16x32_bf16 v[96:99], v[196:199], v[158:161], v[96:99]
	v_mfma_f32_16x16x32_bf16 v[124:127], v[170:173], v[154:157], v[124:127]
	v_mfma_f32_16x16x32_bf16 v[120:123], v[170:173], v[162:165], v[120:123]
	v_mfma_f32_16x16x32_bf16 v[116:119], v[178:181], v[154:157], v[116:119]
	v_mfma_f32_16x16x32_bf16 v[112:115], v[178:181], v[162:165], v[112:115]
	v_mfma_f32_16x16x32_bf16 v[108:111], v[186:189], v[154:157], v[108:111]
	v_mfma_f32_16x16x32_bf16 v[104:107], v[186:189], v[162:165], v[104:107]
	v_mfma_f32_16x16x32_bf16 v[100:103], v[200:203], v[154:157], v[100:103]
	v_mfma_f32_16x16x32_bf16 v[96:99], v[200:203], v[162:165], v[96:99]
	s_barrier
	s_add_u32 s54, s73, 0x180
	s_addc_u32 s55, s74, 0
	v_add_u32_e32 v145, s89, v136
	s_add_i32 m0, s9, s93
	ds_read_b128 v[204:207], v145
	ds_read_b128 v[208:211], v145 offset:1024
	ds_read_b128 v[212:215], v145 offset:2048
	ds_read_b128 v[216:219], v145 offset:3072
	global_load_lds_dwordx4 v192, s[54:55]
	s_add_u32 s14, s54, s6
	s_addc_u32 s15, s55, s7
	s_add_i32 m0, s9, s93
	s_add_i32 m0, m0, 0x2000
	s_nop 0
	global_load_lds_dwordx4 v192, s[14:15]
	s_barrier
	s_waitcnt lgkmcnt(0)
	s_waitcnt lgkmcnt(0)
	v_mfma_f32_16x16x32_bf16 v[92:95], v[166:169], v[204:207], v[92:95]
	v_mfma_f32_16x16x32_bf16 v[88:91], v[166:169], v[212:215], v[88:91]
	v_mfma_f32_16x16x32_bf16 v[84:87], v[174:177], v[204:207], v[84:87]
	v_mfma_f32_16x16x32_bf16 v[80:83], v[174:177], v[212:215], v[80:83]
	v_mfma_f32_16x16x32_bf16 v[76:79], v[182:185], v[204:207], v[76:79]
	v_mfma_f32_16x16x32_bf16 v[72:75], v[182:185], v[212:215], v[72:75]
	v_mfma_f32_16x16x32_bf16 v[68:71], v[196:199], v[204:207], v[68:71]
	v_mfma_f32_16x16x32_bf16 v[64:67], v[196:199], v[212:215], v[64:67]
	v_mfma_f32_16x16x32_bf16 v[92:95], v[170:173], v[208:211], v[92:95]
	v_mfma_f32_16x16x32_bf16 v[88:91], v[170:173], v[216:219], v[88:91]
	v_mfma_f32_16x16x32_bf16 v[84:87], v[178:181], v[208:211], v[84:87]
	v_mfma_f32_16x16x32_bf16 v[80:83], v[178:181], v[216:219], v[80:83]
	v_mfma_f32_16x16x32_bf16 v[76:79], v[186:189], v[208:211], v[76:79]
	v_mfma_f32_16x16x32_bf16 v[72:75], v[186:189], v[216:219], v[72:75]
	v_mfma_f32_16x16x32_bf16 v[68:71], v[200:203], v[208:211], v[68:71]
	v_mfma_f32_16x16x32_bf16 v[64:67], v[200:203], v[216:219], v[64:67]
	s_add_u32 s54, s75, 0x180
	s_addc_u32 s55, s78, 0
	s_add_i32 m0, s9, 0x8000
	s_barrier
	ds_read_b128 v[166:169], v148 offset:49152
	ds_read_b128 v[170:173], v148 offset:50176
	ds_read_b128 v[174:177], v148 offset:51200
	ds_read_b128 v[178:181], v148 offset:52224
	ds_read_b128 v[182:185], v148 offset:53248
	ds_read_b128 v[186:189], v148 offset:54272
	ds_read_b128 v[196:199], v148 offset:55296
	ds_read_b128 v[200:203], v148 offset:56320
	global_load_lds_dwordx4 v192, s[54:55]
	s_add_u32 s14, s54, s6
	s_addc_u32 s15, s55, s7
	s_add_i32 m0, s9, 0xa000
	s_nop 0
	global_load_lds_dwordx4 v192, s[14:15]
	s_barrier
	s_waitcnt lgkmcnt(0)
	s_waitcnt lgkmcnt(0)
	v_mfma_f32_16x16x32_bf16 v[60:63], v[166:169], v[150:153], v[60:63]
	v_mfma_f32_16x16x32_bf16 v[56:59], v[166:169], v[158:161], v[56:59]
	v_mfma_f32_16x16x32_bf16 v[52:55], v[174:177], v[150:153], v[52:55]
	v_mfma_f32_16x16x32_bf16 v[48:51], v[174:177], v[158:161], v[48:51]
	v_mfma_f32_16x16x32_bf16 v[44:47], v[182:185], v[150:153], v[44:47]
	v_mfma_f32_16x16x32_bf16 v[40:43], v[182:185], v[158:161], v[40:43]
	v_mfma_f32_16x16x32_bf16 v[36:39], v[196:199], v[150:153], v[36:39]
	v_mfma_f32_16x16x32_bf16 v[32:35], v[196:199], v[158:161], v[32:35]
	v_mfma_f32_16x16x32_bf16 v[60:63], v[170:173], v[154:157], v[60:63]
	v_mfma_f32_16x16x32_bf16 v[56:59], v[170:173], v[162:165], v[56:59]
	v_mfma_f32_16x16x32_bf16 v[52:55], v[178:181], v[154:157], v[52:55]
	v_mfma_f32_16x16x32_bf16 v[48:51], v[178:181], v[162:165], v[48:51]
	v_mfma_f32_16x16x32_bf16 v[44:47], v[186:189], v[154:157], v[44:47]
	v_mfma_f32_16x16x32_bf16 v[40:43], v[186:189], v[162:165], v[40:43]
	v_mfma_f32_16x16x32_bf16 v[36:39], v[200:203], v[154:157], v[36:39]
	v_mfma_f32_16x16x32_bf16 v[32:35], v[200:203], v[162:165], v[32:35]
	s_barrier
	s_add_u32 s54, s79, 0x180
	s_addc_u32 s55, s80, 0
	s_add_i32 m0, s9, s89
	s_nop 0
	global_load_lds_dwordx4 v192, s[54:55]
	s_add_u32 s14, s54, s6
	s_addc_u32 s15, s55, s7
	s_add_i32 m0, s9, s89
	s_add_i32 m0, m0, 0x2000
	s_nop 0
	global_load_lds_dwordx4 v192, s[14:15]
	s_waitcnt vmcnt(6)
	s_barrier
	v_mfma_f32_16x16x32_bf16 v[28:31], v[166:169], v[204:207], v[28:31]
	v_mfma_f32_16x16x32_bf16 v[24:27], v[166:169], v[212:215], v[24:27]
	v_mfma_f32_16x16x32_bf16 v[20:23], v[174:177], v[204:207], v[20:23]
	v_mfma_f32_16x16x32_bf16 v[16:19], v[174:177], v[212:215], v[16:19]
	v_mfma_f32_16x16x32_bf16 v[12:15], v[182:185], v[204:207], v[12:15]
	v_mfma_f32_16x16x32_bf16 v[8:11], v[182:185], v[212:215], v[8:11]
	v_mfma_f32_16x16x32_bf16 v[4:7], v[196:199], v[204:207], v[4:7]
	v_mfma_f32_16x16x32_bf16 v[0:3], v[196:199], v[212:215], v[0:3]
	v_mfma_f32_16x16x32_bf16 v[28:31], v[170:173], v[208:211], v[28:31]
	v_mfma_f32_16x16x32_bf16 v[24:27], v[170:173], v[216:219], v[24:27]
	v_mfma_f32_16x16x32_bf16 v[20:23], v[178:181], v[208:211], v[20:23]
	v_mfma_f32_16x16x32_bf16 v[16:19], v[178:181], v[216:219], v[16:19]
	v_mfma_f32_16x16x32_bf16 v[12:15], v[186:189], v[208:211], v[12:15]
	v_mfma_f32_16x16x32_bf16 v[8:11], v[186:189], v[216:219], v[8:11]
	v_mfma_f32_16x16x32_bf16 v[4:7], v[200:203], v[208:211], v[4:7]
	v_mfma_f32_16x16x32_bf16 v[0:3], v[200:203], v[216:219], v[0:3]
	s_add_i32 s52, s52, 2
	s_add_u32 s38, s38, 0x100
	s_addc_u32 s39, s39, 0
	s_cmp_lt_u32 s52, 4
	s_barrier
	s_cbranch_scc1 .LBB0_830
	v_add_u32_e32 v149, 0, v136
	s_add_u32 s0, s12, 0x380
	v_add_u32_e32 v140, 0x10000, v149
	s_addc_u32 s1, s13, 0
	ds_read_b128 v[128:131], v140
	ds_read_b128 v[132:135], v140 offset:1024
	ds_read_b128 v[136:139], v140 offset:2048
	ds_read_b128 v[150:153], v140 offset:3072
	ds_read_b128 v[154:157], v148
	ds_read_b128 v[158:161], v148 offset:1024
	ds_read_b128 v[162:165], v148 offset:2048
	ds_read_b128 v[166:169], v148 offset:3072
	ds_read_b128 v[170:173], v148 offset:4096
	ds_read_b128 v[174:177], v148 offset:5120
	ds_read_b128 v[178:181], v148 offset:6144
	ds_read_b128 v[182:185], v148 offset:7168
	v_lshl_add_u64 v[140:141], s[0:1], 0, v[192:193]
	v_readfirstlane_b32 s0, v143
	s_mov_b32 m0, s0
	v_readfirstlane_b32 s0, v144
	global_load_lds_dwordx4 v[140:141], off
	v_lshl_add_u64 v[140:141], v[140:141], 0, s[6:7]
	s_mov_b32 m0, s0
	s_nop 0
	global_load_lds_dwordx4 v[140:141], off
	s_barrier
	s_waitcnt lgkmcnt(0)
	s_waitcnt lgkmcnt(0)
	v_mfma_f32_16x16x32_bf16 v[124:127], v[154:157], v[128:131], v[124:127]
	v_mfma_f32_16x16x32_bf16 v[120:123], v[154:157], v[136:139], v[120:123]
	v_mfma_f32_16x16x32_bf16 v[116:119], v[162:165], v[128:131], v[116:119]
	v_mfma_f32_16x16x32_bf16 v[112:115], v[162:165], v[136:139], v[112:115]
	v_mfma_f32_16x16x32_bf16 v[108:111], v[170:173], v[128:131], v[108:111]
	v_mfma_f32_16x16x32_bf16 v[104:107], v[170:173], v[136:139], v[104:107]
	v_mfma_f32_16x16x32_bf16 v[100:103], v[178:181], v[128:131], v[100:103]
	v_mfma_f32_16x16x32_bf16 v[124:127], v[158:161], v[132:135], v[124:127]
	v_mfma_f32_16x16x32_bf16 v[120:123], v[158:161], v[150:153], v[120:123]
	v_mfma_f32_16x16x32_bf16 v[140:143], v[166:169], v[132:135], v[116:119]
	v_mfma_f32_16x16x32_bf16 v[112:115], v[166:169], v[150:153], v[112:115]
	v_mfma_f32_16x16x32_bf16 v[108:111], v[174:177], v[132:135], v[108:111]
	v_mfma_f32_16x16x32_bf16 v[104:107], v[174:177], v[150:153], v[104:107]
	v_mfma_f32_16x16x32_bf16 v[144:147], v[182:185], v[132:135], v[100:103]
	v_mfma_f32_16x16x32_bf16 v[96:99], v[178:181], v[136:139], v[96:99]
	v_mfma_f32_16x16x32_bf16 v[186:189], v[182:185], v[150:153], v[96:99]
	v_add_u32_e32 v190, 0x14000, v149
	s_barrier
	s_nop 3
	ds_read_b128 v[96:99], v190
	ds_read_b128 v[100:103], v190 offset:1024
	ds_read_b128 v[116:119], v190 offset:2048
	ds_read_b128 v[196:199], v190 offset:3072
	s_barrier
	s_waitcnt lgkmcnt(0)
	s_waitcnt lgkmcnt(0)
	v_mfma_f32_16x16x32_bf16 v[92:95], v[154:157], v[96:99], v[92:95]
	v_mfma_f32_16x16x32_bf16 v[88:91], v[154:157], v[116:119], v[88:91]
	v_mfma_f32_16x16x32_bf16 v[84:87], v[162:165], v[96:99], v[84:87]
	v_mfma_f32_16x16x32_bf16 v[80:83], v[162:165], v[116:119], v[80:83]
	v_mfma_f32_16x16x32_bf16 v[76:79], v[170:173], v[96:99], v[76:79]
	v_mfma_f32_16x16x32_bf16 v[72:75], v[170:173], v[116:119], v[72:75]
	v_mfma_f32_16x16x32_bf16 v[68:71], v[178:181], v[96:99], v[68:71]
	v_mfma_f32_16x16x32_bf16 v[64:67], v[178:181], v[116:119], v[64:67]
	v_mfma_f32_16x16x32_bf16 v[200:203], v[158:161], v[100:103], v[92:95]
	v_mfma_f32_16x16x32_bf16 v[156:159], v[158:161], v[196:199], v[88:91]
	v_mfma_f32_16x16x32_bf16 v[84:87], v[166:169], v[100:103], v[84:87]
	v_mfma_f32_16x16x32_bf16 v[80:83], v[166:169], v[196:199], v[80:83]
	v_mfma_f32_16x16x32_bf16 v[76:79], v[174:177], v[100:103], v[76:79]
	v_mfma_f32_16x16x32_bf16 v[72:75], v[174:177], v[196:199], v[72:75]
	v_mfma_f32_16x16x32_bf16 v[68:71], v[182:185], v[100:103], v[68:71]
	v_mfma_f32_16x16x32_bf16 v[64:67], v[182:185], v[196:199], v[64:67]
	s_barrier
	ds_read_b128 v[88:91], v148 offset:16384
	ds_read_b128 v[92:95], v148 offset:17408
	ds_read_b128 v[160:163], v148 offset:18432
	ds_read_b128 v[164:167], v148 offset:19456
	ds_read_b128 v[168:171], v148 offset:20480
	ds_read_b128 v[172:175], v148 offset:21504
	ds_read_b128 v[176:179], v148 offset:22528
	ds_read_b128 v[180:183], v148 offset:23552
	s_waitcnt vmcnt(4)
	s_barrier
	s_waitcnt lgkmcnt(0)
	s_waitcnt lgkmcnt(0)
	v_mfma_f32_16x16x32_bf16 v[60:63], v[88:91], v[128:131], v[60:63]
	v_mfma_f32_16x16x32_bf16 v[56:59], v[88:91], v[136:139], v[56:59]
	v_mfma_f32_16x16x32_bf16 v[52:55], v[160:163], v[128:131], v[52:55]
	v_mfma_f32_16x16x32_bf16 v[48:51], v[160:163], v[136:139], v[48:51]
	v_mfma_f32_16x16x32_bf16 v[44:47], v[168:171], v[128:131], v[44:47]
	v_mfma_f32_16x16x32_bf16 v[40:43], v[168:171], v[136:139], v[40:43]
	v_mfma_f32_16x16x32_bf16 v[36:39], v[176:179], v[128:131], v[36:39]
	v_mfma_f32_16x16x32_bf16 v[32:35], v[176:179], v[136:139], v[32:35]
	v_mfma_f32_16x16x32_bf16 v[60:63], v[92:95], v[132:135], v[60:63]
	v_mfma_f32_16x16x32_bf16 v[56:59], v[92:95], v[150:153], v[56:59]
	v_mfma_f32_16x16x32_bf16 v[52:55], v[164:167], v[132:135], v[52:55]
	v_mfma_f32_16x16x32_bf16 v[48:51], v[164:167], v[150:153], v[48:51]
	v_mfma_f32_16x16x32_bf16 v[44:47], v[172:175], v[132:135], v[44:47]
	v_mfma_f32_16x16x32_bf16 v[40:43], v[172:175], v[150:153], v[40:43]
	v_mfma_f32_16x16x32_bf16 v[36:39], v[180:183], v[132:135], v[36:39]
	v_mfma_f32_16x16x32_bf16 v[32:35], v[180:183], v[150:153], v[32:35]
	v_mfma_f32_16x16x32_bf16 v[28:31], v[88:91], v[96:99], v[28:31]
	v_mfma_f32_16x16x32_bf16 v[24:27], v[88:91], v[116:119], v[24:27]
	v_mfma_f32_16x16x32_bf16 v[20:23], v[160:163], v[96:99], v[20:23]
	v_mfma_f32_16x16x32_bf16 v[16:19], v[160:163], v[116:119], v[16:19]
	v_mfma_f32_16x16x32_bf16 v[12:15], v[168:171], v[96:99], v[12:15]
	v_mfma_f32_16x16x32_bf16 v[8:11], v[168:171], v[116:119], v[8:11]
	v_mfma_f32_16x16x32_bf16 v[4:7], v[176:179], v[96:99], v[4:7]
	v_mfma_f32_16x16x32_bf16 v[0:3], v[176:179], v[116:119], v[0:3]
	v_mfma_f32_16x16x32_bf16 v[204:207], v[92:95], v[100:103], v[28:31]
	v_mfma_f32_16x16x32_bf16 v[208:211], v[92:95], v[196:199], v[24:27]
	v_mfma_f32_16x16x32_bf16 v[212:215], v[164:167], v[100:103], v[20:23]
	v_mfma_f32_16x16x32_bf16 v[160:163], v[164:167], v[196:199], v[16:19]
	v_mfma_f32_16x16x32_bf16 v[164:167], v[172:175], v[100:103], v[12:15]
	v_mfma_f32_16x16x32_bf16 v[168:171], v[172:175], v[196:199], v[8:11]
	v_mfma_f32_16x16x32_bf16 v[172:175], v[180:183], v[100:103], v[4:7]
	v_mfma_f32_16x16x32_bf16 v[176:179], v[180:183], v[196:199], v[0:3]
	s_nop 1
	v_add_u32_e32 v0, 0x18000, v149
	s_barrier
	ds_read_b128 v[24:27], v0
	ds_read_b128 v[28:31], v0 offset:1024
	ds_read_b128 v[180:183], v0 offset:2048
	ds_read_b128 v[196:199], v0 offset:3072
	ds_read_b128 v[0:3], v148 offset:32768
	ds_read_b128 v[4:7], v148 offset:33792
	ds_read_b128 v[8:11], v148 offset:34816
	ds_read_b128 v[12:15], v148 offset:35840
	ds_read_b128 v[16:19], v148 offset:36864
	ds_read_b128 v[20:23], v148 offset:37888
	ds_read_b128 v[216:219], v148 offset:38912
	ds_read_b128 v[220:223], v148 offset:39936
	s_waitcnt vmcnt(2)
	s_barrier
	s_waitcnt lgkmcnt(0)
	s_waitcnt lgkmcnt(0)
	v_mfma_f32_16x16x32_bf16 v[88:91], v[0:3], v[24:27], v[124:127]
	v_mfma_f32_16x16x32_bf16 v[116:119], v[4:7], v[28:31], v[88:91]
	v_mfma_f32_16x16x32_bf16 v[88:91], v[0:3], v[180:183], v[120:123]
	v_mfma_f32_16x16x32_bf16 v[92:95], v[8:11], v[24:27], v[140:143]
	v_mfma_f32_16x16x32_bf16 v[96:99], v[8:11], v[180:183], v[112:115]
	v_mfma_f32_16x16x32_bf16 v[100:103], v[16:19], v[24:27], v[108:111]
	v_mfma_f32_16x16x32_bf16 v[104:107], v[16:19], v[180:183], v[104:107]
	v_mfma_f32_16x16x32_bf16 v[108:111], v[216:219], v[24:27], v[144:147]
	v_mfma_f32_16x16x32_bf16 v[112:115], v[216:219], v[180:183], v[186:189]
	v_mfma_f32_16x16x32_bf16 v[88:91], v[4:7], v[196:199], v[88:91]
	v_mfma_f32_16x16x32_bf16 v[92:95], v[12:15], v[28:31], v[92:95]
	v_mfma_f32_16x16x32_bf16 v[96:99], v[12:15], v[196:199], v[96:99]
	v_mfma_f32_16x16x32_bf16 v[100:103], v[20:23], v[28:31], v[100:103]
	v_mfma_f32_16x16x32_bf16 v[104:107], v[20:23], v[196:199], v[104:107]
	v_mfma_f32_16x16x32_bf16 v[108:111], v[220:223], v[28:31], v[108:111]
	v_mfma_f32_16x16x32_bf16 v[112:115], v[220:223], v[196:199], v[112:115]
	v_add_u32_e32 v120, 0x1c000, v149
	s_barrier
	ds_read_b128 v[184:187], v120
	ds_read_b128 v[188:191], v120 offset:1024
	ds_read_b128 v[224:227], v120 offset:2048
	ds_read_b128 v[228:231], v120 offset:3072
	s_waitcnt vmcnt(0)
	s_barrier
	s_waitcnt lgkmcnt(0)
	s_waitcnt lgkmcnt(0)
	v_mfma_f32_16x16x32_bf16 v[120:123], v[0:3], v[184:187], v[200:203]
	v_mfma_f32_16x16x32_bf16 v[0:3], v[0:3], v[224:227], v[156:159]
	v_mfma_f32_16x16x32_bf16 v[152:155], v[4:7], v[188:191], v[120:123]
	v_mfma_f32_16x16x32_bf16 v[120:123], v[4:7], v[228:231], v[0:3]
	v_mfma_f32_16x16x32_bf16 v[0:3], v[8:11], v[184:187], v[84:87]
	v_mfma_f32_16x16x32_bf16 v[124:127], v[12:15], v[188:191], v[0:3]
	v_mfma_f32_16x16x32_bf16 v[0:3], v[8:11], v[224:227], v[80:83]
	v_mfma_f32_16x16x32_bf16 v[128:131], v[12:15], v[228:231], v[0:3]
	v_mfma_f32_16x16x32_bf16 v[0:3], v[16:19], v[184:187], v[76:79]
	v_mfma_f32_16x16x32_bf16 v[132:135], v[20:23], v[188:191], v[0:3]
	v_mfma_f32_16x16x32_bf16 v[0:3], v[16:19], v[224:227], v[72:75]
	v_mfma_f32_16x16x32_bf16 v[136:139], v[20:23], v[228:231], v[0:3]
	v_mfma_f32_16x16x32_bf16 v[0:3], v[216:219], v[184:187], v[68:71]
	v_mfma_f32_16x16x32_bf16 v[140:143], v[220:223], v[188:191], v[0:3]
	v_mfma_f32_16x16x32_bf16 v[0:3], v[216:219], v[224:227], v[64:67]
	v_mfma_f32_16x16x32_bf16 v[144:147], v[220:223], v[228:231], v[0:3]
	s_barrier
	ds_read_b128 v[64:67], v148 offset:49152
	ds_read_b128 v[68:71], v148 offset:50176
	ds_read_b128 v[72:75], v148 offset:51200
	ds_read_b128 v[76:79], v148 offset:52224
	ds_read_b128 v[80:83], v148 offset:53248
	ds_read_b128 v[84:87], v148 offset:54272
	ds_read_b128 v[156:159], v148 offset:55296
	ds_read_b128 v[148:151], v148 offset:56320
	s_barrier
	s_waitcnt lgkmcnt(0)
	s_waitcnt lgkmcnt(0)
	v_mfma_f32_16x16x32_bf16 v[0:3], v[64:67], v[24:27], v[60:63]
	v_mfma_f32_16x16x32_bf16 v[8:11], v[72:75], v[24:27], v[52:55]
	v_mfma_f32_16x16x32_bf16 v[16:19], v[80:83], v[24:27], v[44:47]
	v_mfma_f32_16x16x32_bf16 v[24:27], v[156:159], v[24:27], v[36:39]
	v_mfma_f32_16x16x32_bf16 v[0:3], v[68:71], v[28:31], v[0:3]
	v_mfma_f32_16x16x32_bf16 v[4:7], v[64:67], v[180:183], v[56:59]
	v_mfma_f32_16x16x32_bf16 v[8:11], v[76:79], v[28:31], v[8:11]
	v_mfma_f32_16x16x32_bf16 v[12:15], v[72:75], v[180:183], v[48:51]
	v_mfma_f32_16x16x32_bf16 v[16:19], v[84:87], v[28:31], v[16:19]
	v_mfma_f32_16x16x32_bf16 v[20:23], v[80:83], v[180:183], v[40:43]
	v_mfma_f32_16x16x32_bf16 v[24:27], v[148:151], v[28:31], v[24:27]
	v_mfma_f32_16x16x32_bf16 v[28:31], v[156:159], v[180:183], v[32:35]
	v_mfma_f32_16x16x32_bf16 v[4:7], v[68:71], v[196:199], v[4:7]
	v_mfma_f32_16x16x32_bf16 v[12:15], v[76:79], v[196:199], v[12:15]
	v_mfma_f32_16x16x32_bf16 v[20:23], v[84:87], v[196:199], v[20:23]
	v_mfma_f32_16x16x32_bf16 v[28:31], v[148:151], v[196:199], v[28:31]
	v_mfma_f32_16x16x32_bf16 v[32:35], v[64:67], v[184:187], v[204:207]
	v_mfma_f32_16x16x32_bf16 v[36:39], v[64:67], v[224:227], v[208:211]
	v_mfma_f32_16x16x32_bf16 v[40:43], v[72:75], v[184:187], v[212:215]
	v_mfma_f32_16x16x32_bf16 v[44:47], v[72:75], v[224:227], v[160:163]
	v_mfma_f32_16x16x32_bf16 v[48:51], v[80:83], v[184:187], v[164:167]
	v_mfma_f32_16x16x32_bf16 v[52:55], v[80:83], v[224:227], v[168:171]
	v_mfma_f32_16x16x32_bf16 v[56:59], v[156:159], v[184:187], v[172:175]
	v_mfma_f32_16x16x32_bf16 v[60:63], v[156:159], v[224:227], v[176:179]
	v_mfma_f32_16x16x32_bf16 v[32:35], v[68:71], v[188:191], v[32:35]
	v_mfma_f32_16x16x32_bf16 v[36:39], v[68:71], v[228:231], v[36:39]
	v_mfma_f32_16x16x32_bf16 v[40:43], v[76:79], v[188:191], v[40:43]
	v_mfma_f32_16x16x32_bf16 v[44:47], v[76:79], v[228:231], v[44:47]
	v_mfma_f32_16x16x32_bf16 v[48:51], v[84:87], v[188:191], v[48:51]
	v_mfma_f32_16x16x32_bf16 v[52:55], v[84:87], v[228:231], v[52:55]
	v_mfma_f32_16x16x32_bf16 v[56:59], v[148:151], v[188:191], v[56:59]
	v_mfma_f32_16x16x32_bf16 v[60:63], v[148:151], v[228:231], v[60:63]
	s_cmpk_gt_u32 s47, 0xff
	s_barrier
	s_cbranch_scc1 .LBB0_833
	s_barrier

.LBB0_835:
	v_and_b32_e32 v2, 15, v1
	v_and_b32_e32 v3, 48, v1
	v_lshlrev_b32_e32 v2, 6, v2
	v_lshlrev_b32_e32 v1, 2, v1
	v_or_b32_e32 v4, v2, v3
	v_and_b32_e32 v1, 32, v1
	s_lshl_b32 s38, s38, 13
	v_bitop3_b32 v4, v4, s38, v1 bitop3:0xde
	s_lshl_b32 s38, s52, 6
	v_bitop3_b32 v2, v2, v1, v3 bitop3:0x36
	s_and_b32 s38, s38, 0x3000
	v_or_b32_e32 v136, s38, v2
	s_add_u32 s38, s0, 0x80
	s_addc_u32 s39, s1, 0
	v_add_u32_e32 v137, s93, v0
	v_lshl_add_u64 v[2:3], s[38:39], 0, v[192:193]
	v_readfirstlane_b32 s38, v137
	v_add_u32_e32 v138, 0x2000, v137
	s_mov_b32 m0, s38
	v_readfirstlane_b32 s38, v138
	s_waitcnt vmcnt(4)
	s_barrier
	global_load_lds_dwordx4 v[2:3], off
	s_mov_b32 m0, s38
	s_add_u32 s38, s2, 0x80
	v_lshl_add_u64 v[2:3], v[2:3], 0, s[6:7]
	s_addc_u32 s39, s3, 0
	v_add_u32_e32 v139, 0x8000, v130
	global_load_lds_dwordx4 v[2:3], off
	v_lshl_add_u64 v[2:3], s[38:39], 0, v[192:193]
	v_readfirstlane_b32 s38, v139
	v_add_u32_e32 v140, 0xa000, v130
	s_mov_b32 m0, s38
	v_readfirstlane_b32 s38, v140
	global_load_lds_dwordx4 v[2:3], off
	s_mov_b32 m0, s38
	s_add_u32 s38, s36, 0x80
	v_lshl_add_u64 v[2:3], v[2:3], 0, s[6:7]
	s_addc_u32 s39, s37, 0
	v_add_u32_e32 v141, s89, v0
	global_load_lds_dwordx4 v[2:3], off
	v_lshl_add_u64 v[2:3], s[38:39], 0, v[192:193]
	v_readfirstlane_b32 s38, v141
	v_add_u32_e32 v142, 0x2000, v141
	s_mov_b32 m0, s38
	v_readfirstlane_b32 s38, v142
	global_load_lds_dwordx4 v[2:3], off
	v_lshl_add_u64 v[0:1], v[2:3], 0, s[6:7]
	s_mov_b32 m0, s38
	s_mov_b32 s48, -2
	global_load_lds_dwordx4 v[0:1], off
	s_waitcnt vmcnt(6)
	v_mov_b32_e32 v0, 0
	s_mov_b64 s[38:39], 0
	v_add_u32_e32 v144, 0, v4
	v_mov_b32_e32 v1, v0
	v_mov_b32_e32 v2, v0
	v_mov_b32_e32 v3, v0
	v_mov_b32_e32 v4, v0
	v_mov_b32_e32 v5, v0
	v_mov_b32_e32 v6, v0
	v_mov_b32_e32 v7, v0
	v_mov_b32_e32 v8, v0
	v_mov_b32_e32 v9, v0
	v_mov_b32_e32 v10, v0
	v_mov_b32_e32 v11, v0
	v_mov_b32_e32 v12, v0
	v_mov_b32_e32 v13, v0
	v_mov_b32_e32 v14, v0
	v_mov_b32_e32 v15, v0
	v_mov_b32_e32 v16, v0
	v_mov_b32_e32 v17, v0
	v_mov_b32_e32 v18, v0
	v_mov_b32_e32 v19, v0
	v_mov_b32_e32 v20, v0
	v_mov_b32_e32 v21, v0
	v_mov_b32_e32 v22, v0
	v_mov_b32_e32 v23, v0
	v_mov_b32_e32 v24, v0
	v_mov_b32_e32 v25, v0
	v_mov_b32_e32 v26, v0
	v_mov_b32_e32 v27, v0
	v_mov_b32_e32 v28, v0
	v_mov_b32_e32 v29, v0
	v_mov_b32_e32 v30, v0
	v_mov_b32_e32 v31, v0
	v_mov_b32_e32 v32, v0
	v_mov_b32_e32 v33, v0
	v_mov_b32_e32 v34, v0
	v_mov_b32_e32 v35, v0
	v_mov_b32_e32 v36, v0
	v_mov_b32_e32 v37, v0
	v_mov_b32_e32 v38, v0
	v_mov_b32_e32 v39, v0
	v_mov_b32_e32 v40, v0
	v_mov_b32_e32 v41, v0
	v_mov_b32_e32 v42, v0
	v_mov_b32_e32 v43, v0
	v_mov_b32_e32 v44, v0
	v_mov_b32_e32 v45, v0
	v_mov_b32_e32 v46, v0
	v_mov_b32_e32 v47, v0
	v_mov_b32_e32 v48, v0
	v_mov_b32_e32 v49, v0
	v_mov_b32_e32 v50, v0
	v_mov_b32_e32 v51, v0
	v_mov_b32_e32 v52, v0
	v_mov_b32_e32 v53, v0
	v_mov_b32_e32 v54, v0
	v_mov_b32_e32 v55, v0
	v_mov_b32_e32 v56, v0
	v_mov_b32_e32 v57, v0
	v_mov_b32_e32 v58, v0
	v_mov_b32_e32 v59, v0
	v_mov_b32_e32 v60, v0
	v_mov_b32_e32 v61, v0
	v_mov_b32_e32 v62, v0
	v_mov_b32_e32 v63, v0
	v_mov_b32_e32 v64, v0
	v_mov_b32_e32 v65, v0
	v_mov_b32_e32 v66, v0
	v_mov_b32_e32 v67, v0
	v_mov_b32_e32 v68, v0
	v_mov_b32_e32 v69, v0
	v_mov_b32_e32 v70, v0
	v_mov_b32_e32 v71, v0
	v_mov_b32_e32 v72, v0
	v_mov_b32_e32 v73, v0
	v_mov_b32_e32 v74, v0
	v_mov_b32_e32 v75, v0
	v_mov_b32_e32 v76, v0
	v_mov_b32_e32 v77, v0
	v_mov_b32_e32 v78, v0
	v_mov_b32_e32 v79, v0
	v_mov_b32_e32 v80, v0
	v_mov_b32_e32 v81, v0
	v_mov_b32_e32 v82, v0
	v_mov_b32_e32 v83, v0
	v_mov_b32_e32 v84, v0
	v_mov_b32_e32 v85, v0
	v_mov_b32_e32 v86, v0
	v_mov_b32_e32 v87, v0
	v_mov_b32_e32 v88, v0
	v_mov_b32_e32 v89, v0
	v_mov_b32_e32 v90, v0
	v_mov_b32_e32 v91, v0
	v_mov_b32_e32 v92, v0
	v_mov_b32_e32 v93, v0
	v_mov_b32_e32 v94, v0
	v_mov_b32_e32 v95, v0
	v_mov_b32_e32 v96, v0
	v_mov_b32_e32 v97, v0
	v_mov_b32_e32 v98, v0
	v_mov_b32_e32 v99, v0
	v_mov_b32_e32 v100, v0
	v_mov_b32_e32 v101, v0
	v_mov_b32_e32 v102, v0
	v_mov_b32_e32 v103, v0
	v_mov_b32_e32 v104, v0
	v_mov_b32_e32 v105, v0
	v_mov_b32_e32 v106, v0
	v_mov_b32_e32 v107, v0
	v_mov_b32_e32 v108, v0
	v_mov_b32_e32 v109, v0
	v_mov_b32_e32 v110, v0
	v_mov_b32_e32 v111, v0
	v_mov_b32_e32 v112, v0
	v_mov_b32_e32 v113, v0
	v_mov_b32_e32 v114, v0
	v_mov_b32_e32 v115, v0
	v_mov_b32_e32 v116, v0
	v_mov_b32_e32 v117, v0
	v_mov_b32_e32 v118, v0
	v_mov_b32_e32 v119, v0
	v_mov_b32_e32 v120, v0
	v_mov_b32_e32 v121, v0
	v_mov_b32_e32 v122, v0
	v_mov_b32_e32 v123, v0
	v_mov_b32_e32 v124, v0
	v_mov_b32_e32 v125, v0
	v_mov_b32_e32 v126, v0
	v_mov_b32_e32 v127, v0
	s_movk_i32 s78, 0x600
	s_movk_i32 s79, 0x37f
	v_readfirstlane_b32 s20, v130
	s_barrier
.LBB0_836:
	v_add_u32_e32 v143, s77, v136
	ds_read_b128 v[146:149], v143
	ds_read_b128 v[150:153], v143 offset:1024
	ds_read_b128 v[154:157], v143 offset:2048
	ds_read_b128 v[158:161], v143 offset:3072
	s_add_u32 s49, s12, s38
	s_addc_u32 s53, s13, s39
	s_add_u32 s50, s49, 0x80
	s_addc_u32 s51, s53, 0
	v_add_u32_e32 v143, 0xc000, v130
	v_add_u32_e32 v145, 0xe000, v130
	s_add_i32 m0, s20, 0xc000
	ds_read_b128 v[162:165], v144
	ds_read_b128 v[166:169], v144 offset:1024
	ds_read_b128 v[170:173], v144 offset:2048
	ds_read_b128 v[174:177], v144 offset:3072
	ds_read_b128 v[178:181], v144 offset:4096
	ds_read_b128 v[182:185], v144 offset:5120
	ds_read_b128 v[186:189], v144 offset:6144
	ds_read_b128 v[196:199], v144 offset:7168
	global_load_lds_dwordx4 v192, s[50:51]
	s_add_u32 s18, s50, s6
	s_addc_u32 s19, s51, s7
	s_add_i32 m0, s20, 0xe000
	s_nop 0
	global_load_lds_dwordx4 v192, s[18:19]
	s_waitcnt lgkmcnt(8)
	s_barrier
	s_waitcnt lgkmcnt(0)
	s_waitcnt lgkmcnt(0)
	v_mfma_f32_16x16x32_bf16 v[124:127], v[162:165], v[146:149], v[124:127]
	v_mfma_f32_16x16x32_bf16 v[120:123], v[162:165], v[154:157], v[120:123]
	v_mfma_f32_16x16x32_bf16 v[116:119], v[170:173], v[146:149], v[116:119]
	v_mfma_f32_16x16x32_bf16 v[112:115], v[170:173], v[154:157], v[112:115]
	v_mfma_f32_16x16x32_bf16 v[108:111], v[178:181], v[146:149], v[108:111]
	v_mfma_f32_16x16x32_bf16 v[104:107], v[178:181], v[154:157], v[104:107]
	v_mfma_f32_16x16x32_bf16 v[100:103], v[186:189], v[146:149], v[100:103]
	v_mfma_f32_16x16x32_bf16 v[96:99], v[186:189], v[154:157], v[96:99]
	v_mfma_f32_16x16x32_bf16 v[124:127], v[166:169], v[150:153], v[124:127]
	v_mfma_f32_16x16x32_bf16 v[120:123], v[166:169], v[158:161], v[120:123]
	v_mfma_f32_16x16x32_bf16 v[116:119], v[174:177], v[150:153], v[116:119]
	v_mfma_f32_16x16x32_bf16 v[112:115], v[174:177], v[158:161], v[112:115]
	v_mfma_f32_16x16x32_bf16 v[108:111], v[182:185], v[150:153], v[108:111]
	v_mfma_f32_16x16x32_bf16 v[104:107], v[182:185], v[158:161], v[104:107]
	v_mfma_f32_16x16x32_bf16 v[100:103], v[196:199], v[150:153], v[100:103]
	v_mfma_f32_16x16x32_bf16 v[96:99], v[196:199], v[158:161], v[96:99]
	s_barrier
	s_add_u32 s54, s0, s38
	s_addc_u32 s55, s1, s39
	s_add_u32 s50, s54, 0x100
	v_add_u32_e32 v190, s33, v136
	s_addc_u32 s51, s55, 0
	ds_read_b128 v[200:203], v190
	ds_read_b128 v[204:207], v190 offset:1024
	ds_read_b128 v[208:211], v190 offset:2048
	ds_read_b128 v[212:215], v190 offset:3072
	s_add_i32 m0, s20, s77
	s_nop 0
	global_load_lds_dwordx4 v192, s[50:51]
	s_add_u32 s18, s50, s6
	s_addc_u32 s19, s51, s7
	s_add_i32 m0, s20, s77
	s_add_i32 m0, m0, 0x2000
	s_nop 0
	global_load_lds_dwordx4 v192, s[18:19]
	s_barrier
	s_waitcnt lgkmcnt(0)
	s_waitcnt lgkmcnt(0)
	v_mfma_f32_16x16x32_bf16 v[92:95], v[162:165], v[200:203], v[92:95]
	v_mfma_f32_16x16x32_bf16 v[88:91], v[162:165], v[208:211], v[88:91]
	v_mfma_f32_16x16x32_bf16 v[84:87], v[170:173], v[200:203], v[84:87]
	v_mfma_f32_16x16x32_bf16 v[80:83], v[170:173], v[208:211], v[80:83]
	v_mfma_f32_16x16x32_bf16 v[76:79], v[178:181], v[200:203], v[76:79]
	v_mfma_f32_16x16x32_bf16 v[72:75], v[178:181], v[208:211], v[72:75]
	v_mfma_f32_16x16x32_bf16 v[68:71], v[186:189], v[200:203], v[68:71]
	v_mfma_f32_16x16x32_bf16 v[64:67], v[186:189], v[208:211], v[64:67]
	v_mfma_f32_16x16x32_bf16 v[92:95], v[166:169], v[204:207], v[92:95]
	v_mfma_f32_16x16x32_bf16 v[88:91], v[166:169], v[212:215], v[88:91]
	v_mfma_f32_16x16x32_bf16 v[84:87], v[174:177], v[204:207], v[84:87]
	v_mfma_f32_16x16x32_bf16 v[80:83], v[174:177], v[212:215], v[80:83]
	v_mfma_f32_16x16x32_bf16 v[76:79], v[182:185], v[204:207], v[76:79]
	v_mfma_f32_16x16x32_bf16 v[72:75], v[182:185], v[212:215], v[72:75]
	v_mfma_f32_16x16x32_bf16 v[68:71], v[196:199], v[204:207], v[68:71]
	v_mfma_f32_16x16x32_bf16 v[64:67], v[196:199], v[212:215], v[64:67]
	s_add_u32 s72, s2, s38
	s_addc_u32 s73, s3, s39
	s_add_u32 s50, s72, 0x100
	s_addc_u32 s51, s73, 0
	s_mov_b32 m0, s20
	s_barrier
	ds_read_b128 v[162:165], v144 offset:16384
	ds_read_b128 v[166:169], v144 offset:17408
	ds_read_b128 v[170:173], v144 offset:18432
	ds_read_b128 v[174:177], v144 offset:19456
	ds_read_b128 v[178:181], v144 offset:20480
	ds_read_b128 v[182:185], v144 offset:21504
	ds_read_b128 v[186:189], v144 offset:22528
	ds_read_b128 v[196:199], v144 offset:23552
	global_load_lds_dwordx4 v192, s[50:51]
	s_add_u32 s18, s50, s6
	s_addc_u32 s19, s51, s7
	s_add_i32 m0, s20, 0x2000
	s_nop 0
	global_load_lds_dwordx4 v192, s[18:19]
	s_barrier
	s_waitcnt lgkmcnt(0)
	s_waitcnt lgkmcnt(0)
	v_mfma_f32_16x16x32_bf16 v[60:63], v[162:165], v[146:149], v[60:63]
	v_mfma_f32_16x16x32_bf16 v[56:59], v[162:165], v[154:157], v[56:59]
	v_mfma_f32_16x16x32_bf16 v[52:55], v[170:173], v[146:149], v[52:55]
	v_mfma_f32_16x16x32_bf16 v[48:51], v[170:173], v[154:157], v[48:51]
	v_mfma_f32_16x16x32_bf16 v[44:47], v[178:181], v[146:149], v[44:47]
	v_mfma_f32_16x16x32_bf16 v[40:43], v[178:181], v[154:157], v[40:43]
	v_mfma_f32_16x16x32_bf16 v[36:39], v[186:189], v[146:149], v[36:39]
	v_mfma_f32_16x16x32_bf16 v[32:35], v[186:189], v[154:157], v[32:35]
	v_mfma_f32_16x16x32_bf16 v[60:63], v[166:169], v[150:153], v[60:63]
	v_mfma_f32_16x16x32_bf16 v[56:59], v[166:169], v[158:161], v[56:59]
	v_mfma_f32_16x16x32_bf16 v[52:55], v[174:177], v[150:153], v[52:55]
	v_mfma_f32_16x16x32_bf16 v[48:51], v[174:177], v[158:161], v[48:51]
	v_mfma_f32_16x16x32_bf16 v[44:47], v[182:185], v[150:153], v[44:47]
	v_mfma_f32_16x16x32_bf16 v[40:43], v[182:185], v[158:161], v[40:43]
	v_mfma_f32_16x16x32_bf16 v[36:39], v[196:199], v[150:153], v[36:39]
	v_mfma_f32_16x16x32_bf16 v[32:35], v[196:199], v[158:161], v[32:35]
	s_barrier
	s_add_u32 s74, s36, s38
	s_addc_u32 s75, s37, s39
	s_add_u32 s50, s74, 0x100
	s_addc_u32 s51, s75, 0
	s_add_i32 m0, s20, s33
	s_nop 0
	global_load_lds_dwordx4 v192, s[50:51]
	s_add_u32 s18, s50, s6
	s_addc_u32 s19, s51, s7
	s_add_i32 m0, s20, s33
	s_add_i32 m0, m0, 0x2000
	s_nop 0
	global_load_lds_dwordx4 v192, s[18:19]
	s_waitcnt vmcnt(6)
	s_barrier
	v_mfma_f32_16x16x32_bf16 v[28:31], v[162:165], v[200:203], v[28:31]
	v_mfma_f32_16x16x32_bf16 v[24:27], v[162:165], v[208:211], v[24:27]
	v_mfma_f32_16x16x32_bf16 v[20:23], v[170:173], v[200:203], v[20:23]
	v_mfma_f32_16x16x32_bf16 v[16:19], v[170:173], v[208:211], v[16:19]
	v_mfma_f32_16x16x32_bf16 v[12:15], v[178:181], v[200:203], v[12:15]
	v_mfma_f32_16x16x32_bf16 v[8:11], v[178:181], v[208:211], v[8:11]
	v_mfma_f32_16x16x32_bf16 v[4:7], v[186:189], v[200:203], v[4:7]
	v_mfma_f32_16x16x32_bf16 v[0:3], v[186:189], v[208:211], v[0:3]
	v_mfma_f32_16x16x32_bf16 v[28:31], v[166:169], v[204:207], v[28:31]
	v_mfma_f32_16x16x32_bf16 v[24:27], v[166:169], v[212:215], v[24:27]
	v_mfma_f32_16x16x32_bf16 v[20:23], v[174:177], v[204:207], v[20:23]
	v_mfma_f32_16x16x32_bf16 v[16:19], v[174:177], v[212:215], v[16:19]
	v_mfma_f32_16x16x32_bf16 v[12:15], v[182:185], v[204:207], v[12:15]
	v_mfma_f32_16x16x32_bf16 v[8:11], v[182:185], v[212:215], v[8:11]
	v_mfma_f32_16x16x32_bf16 v[4:7], v[196:199], v[204:207], v[4:7]
	v_mfma_f32_16x16x32_bf16 v[0:3], v[196:199], v[212:215], v[0:3]
	v_add_u32_e32 v158, s93, v136
	s_barrier
	ds_read_b128 v[146:149], v158
	ds_read_b128 v[150:153], v158 offset:1024
	ds_read_b128 v[154:157], v158 offset:2048
	ds_read_b128 v[158:161], v158 offset:3072
	s_add_u32 s50, s49, 0x100
	s_addc_u32 s51, s53, 0
	s_add_i32 m0, s20, 0x4000
	ds_read_b128 v[162:165], v144 offset:32768
	ds_read_b128 v[166:169], v144 offset:33792
	ds_read_b128 v[170:173], v144 offset:34816
	ds_read_b128 v[174:177], v144 offset:35840
	ds_read_b128 v[178:181], v144 offset:36864
	ds_read_b128 v[182:185], v144 offset:37888
	ds_read_b128 v[186:189], v144 offset:38912
	ds_read_b128 v[196:199], v144 offset:39936
	global_load_lds_dwordx4 v192, s[50:51]
	s_add_u32 s18, s50, s6
	s_addc_u32 s19, s51, s7
	s_add_i32 m0, s20, 0x6000
	s_nop 0
	global_load_lds_dwordx4 v192, s[18:19]
	s_waitcnt lgkmcnt(8)
	s_barrier
	s_waitcnt lgkmcnt(0)
	s_waitcnt lgkmcnt(0)
	v_mfma_f32_16x16x32_bf16 v[124:127], v[162:165], v[146:149], v[124:127]
	v_mfma_f32_16x16x32_bf16 v[120:123], v[162:165], v[154:157], v[120:123]
	v_mfma_f32_16x16x32_bf16 v[116:119], v[170:173], v[146:149], v[116:119]
	v_mfma_f32_16x16x32_bf16 v[112:115], v[170:173], v[154:157], v[112:115]
	v_mfma_f32_16x16x32_bf16 v[108:111], v[178:181], v[146:149], v[108:111]
	v_mfma_f32_16x16x32_bf16 v[104:107], v[178:181], v[154:157], v[104:107]
	v_mfma_f32_16x16x32_bf16 v[100:103], v[186:189], v[146:149], v[100:103]
	v_mfma_f32_16x16x32_bf16 v[96:99], v[186:189], v[154:157], v[96:99]
	v_mfma_f32_16x16x32_bf16 v[124:127], v[166:169], v[150:153], v[124:127]
	v_mfma_f32_16x16x32_bf16 v[120:123], v[166:169], v[158:161], v[120:123]
	v_mfma_f32_16x16x32_bf16 v[116:119], v[174:177], v[150:153], v[116:119]
	v_mfma_f32_16x16x32_bf16 v[112:115], v[174:177], v[158:161], v[112:115]
	v_mfma_f32_16x16x32_bf16 v[108:111], v[182:185], v[150:153], v[108:111]
	v_mfma_f32_16x16x32_bf16 v[104:107], v[182:185], v[158:161], v[104:107]
	v_mfma_f32_16x16x32_bf16 v[100:103], v[196:199], v[150:153], v[100:103]
	v_mfma_f32_16x16x32_bf16 v[96:99], v[196:199], v[158:161], v[96:99]
	s_barrier
	s_add_u32 s50, s54, 0x180
	v_add_u32_e32 v190, s89, v136
	s_addc_u32 s51, s55, 0
	ds_read_b128 v[200:203], v190
	ds_read_b128 v[204:207], v190 offset:1024
	ds_read_b128 v[208:211], v190 offset:2048
	ds_read_b128 v[212:215], v190 offset:3072
	s_add_i32 m0, s20, s93
	s_nop 0
	global_load_lds_dwordx4 v192, s[50:51]
	s_add_u32 s18, s50, s6
	s_addc_u32 s19, s51, s7
	s_add_i32 m0, s20, s93
	s_add_i32 m0, m0, 0x2000
	s_nop 0
	global_load_lds_dwordx4 v192, s[18:19]
	s_barrier
	s_waitcnt lgkmcnt(0)
	s_waitcnt lgkmcnt(0)
	v_mfma_f32_16x16x32_bf16 v[92:95], v[162:165], v[200:203], v[92:95]
	v_mfma_f32_16x16x32_bf16 v[88:91], v[162:165], v[208:211], v[88:91]
	v_mfma_f32_16x16x32_bf16 v[84:87], v[170:173], v[200:203], v[84:87]
	v_mfma_f32_16x16x32_bf16 v[80:83], v[170:173], v[208:211], v[80:83]
	v_mfma_f32_16x16x32_bf16 v[76:79], v[178:181], v[200:203], v[76:79]
	v_mfma_f32_16x16x32_bf16 v[72:75], v[178:181], v[208:211], v[72:75]
	v_mfma_f32_16x16x32_bf16 v[68:71], v[186:189], v[200:203], v[68:71]
	v_mfma_f32_16x16x32_bf16 v[64:67], v[186:189], v[208:211], v[64:67]
	v_mfma_f32_16x16x32_bf16 v[92:95], v[166:169], v[204:207], v[92:95]
	v_mfma_f32_16x16x32_bf16 v[88:91], v[166:169], v[212:215], v[88:91]
	v_mfma_f32_16x16x32_bf16 v[84:87], v[174:177], v[204:207], v[84:87]
	v_mfma_f32_16x16x32_bf16 v[80:83], v[174:177], v[212:215], v[80:83]
	v_mfma_f32_16x16x32_bf16 v[76:79], v[182:185], v[204:207], v[76:79]
	v_mfma_f32_16x16x32_bf16 v[72:75], v[182:185], v[212:215], v[72:75]
	v_mfma_f32_16x16x32_bf16 v[68:71], v[196:199], v[204:207], v[68:71]
	v_mfma_f32_16x16x32_bf16 v[64:67], v[196:199], v[212:215], v[64:67]
	s_add_u32 s50, s72, 0x180
	s_addc_u32 s51, s73, 0
	s_add_i32 m0, s20, 0x8000
	s_barrier
	ds_read_b128 v[162:165], v144 offset:49152
	ds_read_b128 v[166:169], v144 offset:50176
	ds_read_b128 v[170:173], v144 offset:51200
	ds_read_b128 v[174:177], v144 offset:52224
	ds_read_b128 v[178:181], v144 offset:53248
	ds_read_b128 v[182:185], v144 offset:54272
	ds_read_b128 v[186:189], v144 offset:55296
	ds_read_b128 v[196:199], v144 offset:56320
	global_load_lds_dwordx4 v192, s[50:51]
	s_add_u32 s18, s50, s6
	s_addc_u32 s19, s51, s7
	s_add_i32 m0, s20, 0xa000
	s_nop 0
	global_load_lds_dwordx4 v192, s[18:19]
	s_barrier
	s_waitcnt lgkmcnt(0)
	s_waitcnt lgkmcnt(0)
	v_mfma_f32_16x16x32_bf16 v[60:63], v[162:165], v[146:149], v[60:63]
	v_mfma_f32_16x16x32_bf16 v[56:59], v[162:165], v[154:157], v[56:59]
	v_mfma_f32_16x16x32_bf16 v[52:55], v[170:173], v[146:149], v[52:55]
	v_mfma_f32_16x16x32_bf16 v[48:51], v[170:173], v[154:157], v[48:51]
	v_mfma_f32_16x16x32_bf16 v[44:47], v[178:181], v[146:149], v[44:47]
	v_mfma_f32_16x16x32_bf16 v[40:43], v[178:181], v[154:157], v[40:43]
	v_mfma_f32_16x16x32_bf16 v[36:39], v[186:189], v[146:149], v[36:39]
	v_mfma_f32_16x16x32_bf16 v[32:35], v[186:189], v[154:157], v[32:35]
	v_mfma_f32_16x16x32_bf16 v[60:63], v[166:169], v[150:153], v[60:63]
	v_mfma_f32_16x16x32_bf16 v[56:59], v[166:169], v[158:161], v[56:59]
	v_mfma_f32_16x16x32_bf16 v[52:55], v[174:177], v[150:153], v[52:55]
	v_mfma_f32_16x16x32_bf16 v[48:51], v[174:177], v[158:161], v[48:51]
	v_mfma_f32_16x16x32_bf16 v[44:47], v[182:185], v[150:153], v[44:47]
	v_mfma_f32_16x16x32_bf16 v[40:43], v[182:185], v[158:161], v[40:43]
	v_mfma_f32_16x16x32_bf16 v[36:39], v[196:199], v[150:153], v[36:39]
	v_mfma_f32_16x16x32_bf16 v[32:35], v[196:199], v[158:161], v[32:35]
	s_barrier
	s_add_u32 s50, s74, 0x180
	s_addc_u32 s51, s75, 0
	s_add_i32 m0, s20, s89
	s_nop 0
	global_load_lds_dwordx4 v192, s[50:51]
	s_add_u32 s18, s50, s6
	s_addc_u32 s19, s51, s7
	s_add_i32 m0, s20, s89
	s_add_i32 m0, m0, 0x2000
	s_nop 0
	global_load_lds_dwordx4 v192, s[18:19]
	s_waitcnt vmcnt(6)
	s_barrier
	v_mfma_f32_16x16x32_bf16 v[28:31], v[162:165], v[200:203], v[28:31]
	v_mfma_f32_16x16x32_bf16 v[24:27], v[162:165], v[208:211], v[24:27]
	v_mfma_f32_16x16x32_bf16 v[20:23], v[170:173], v[200:203], v[20:23]
	v_mfma_f32_16x16x32_bf16 v[16:19], v[170:173], v[208:211], v[16:19]
	v_mfma_f32_16x16x32_bf16 v[12:15], v[178:181], v[200:203], v[12:15]
	v_mfma_f32_16x16x32_bf16 v[8:11], v[178:181], v[208:211], v[8:11]
	v_mfma_f32_16x16x32_bf16 v[4:7], v[186:189], v[200:203], v[4:7]
	v_mfma_f32_16x16x32_bf16 v[0:3], v[186:189], v[208:211], v[0:3]
	v_mfma_f32_16x16x32_bf16 v[28:31], v[166:169], v[204:207], v[28:31]
	v_mfma_f32_16x16x32_bf16 v[24:27], v[166:169], v[212:215], v[24:27]
	v_mfma_f32_16x16x32_bf16 v[20:23], v[174:177], v[204:207], v[20:23]
	v_mfma_f32_16x16x32_bf16 v[16:19], v[174:177], v[212:215], v[16:19]
	v_mfma_f32_16x16x32_bf16 v[12:15], v[182:185], v[204:207], v[12:15]
	v_mfma_f32_16x16x32_bf16 v[8:11], v[182:185], v[212:215], v[8:11]
	v_mfma_f32_16x16x32_bf16 v[4:7], v[196:199], v[204:207], v[4:7]
	v_mfma_f32_16x16x32_bf16 v[0:3], v[196:199], v[212:215], v[0:3]
	s_add_i32 s48, s48, 2
	s_add_u32 s38, s38, 0x100
	s_addc_u32 s39, s39, 0
	s_cmp_lt_u32 s48, 4
	s_barrier
	s_cbranch_scc1 .LBB0_836
	v_add_u32_e32 v195, 0, v136
	s_add_u32 s0, s12, 0x380
	v_add_u32_e32 v140, 0x10000, v195
	s_addc_u32 s1, s13, 0
	ds_read_b128 v[128:131], v140
	ds_read_b128 v[132:135], v140 offset:1024
	ds_read_b128 v[136:139], v140 offset:2048
	ds_read_b128 v[146:149], v140 offset:3072
	ds_read_b128 v[150:153], v144
	ds_read_b128 v[154:157], v144 offset:1024
	ds_read_b128 v[158:161], v144 offset:2048
	ds_read_b128 v[162:165], v144 offset:3072
	ds_read_b128 v[166:169], v144 offset:4096
	ds_read_b128 v[170:173], v144 offset:5120
	ds_read_b128 v[174:177], v144 offset:6144
	ds_read_b128 v[178:181], v144 offset:7168
	v_lshl_add_u64 v[140:141], s[0:1], 0, v[192:193]
	v_readfirstlane_b32 s0, v143
	s_mov_b32 m0, s0
	v_readfirstlane_b32 s0, v145
	global_load_lds_dwordx4 v[140:141], off
	v_lshl_add_u64 v[140:141], v[140:141], 0, s[6:7]
	s_mov_b32 m0, s0
	s_nop 0
	global_load_lds_dwordx4 v[140:141], off
	s_barrier
	s_waitcnt lgkmcnt(0)
	s_waitcnt lgkmcnt(0)
	v_mfma_f32_16x16x32_bf16 v[124:127], v[150:153], v[128:131], v[124:127]
	v_mfma_f32_16x16x32_bf16 v[120:123], v[150:153], v[136:139], v[120:123]
	v_mfma_f32_16x16x32_bf16 v[116:119], v[158:161], v[128:131], v[116:119]
	v_mfma_f32_16x16x32_bf16 v[124:127], v[154:157], v[132:135], v[124:127]
	v_mfma_f32_16x16x32_bf16 v[120:123], v[154:157], v[146:149], v[120:123]
	v_mfma_f32_16x16x32_bf16 v[140:143], v[162:165], v[132:135], v[116:119]
	v_mfma_f32_16x16x32_bf16 v[112:115], v[158:161], v[136:139], v[112:115]
	v_mfma_f32_16x16x32_bf16 v[108:111], v[166:169], v[128:131], v[108:111]
	v_mfma_f32_16x16x32_bf16 v[104:107], v[166:169], v[136:139], v[104:107]
	v_mfma_f32_16x16x32_bf16 v[100:103], v[174:177], v[128:131], v[100:103]
	v_mfma_f32_16x16x32_bf16 v[96:99], v[174:177], v[136:139], v[96:99]
	v_mfma_f32_16x16x32_bf16 v[112:115], v[162:165], v[146:149], v[112:115]
	v_mfma_f32_16x16x32_bf16 v[108:111], v[170:173], v[132:135], v[108:111]
	v_mfma_f32_16x16x32_bf16 v[104:107], v[170:173], v[146:149], v[104:107]
	v_mfma_f32_16x16x32_bf16 v[100:103], v[178:181], v[132:135], v[100:103]
	v_mfma_f32_16x16x32_bf16 v[96:99], v[178:181], v[146:149], v[96:99]
	v_add_u32_e32 v145, 0x14000, v195
	s_barrier
	ds_read_b128 v[116:119], v145
	ds_read_b128 v[182:185], v145 offset:1024
	ds_read_b128 v[186:189], v145 offset:2048
	ds_read_b128 v[196:199], v145 offset:3072
	s_barrier
	s_waitcnt lgkmcnt(0)
	s_waitcnt lgkmcnt(0)
	v_mfma_f32_16x16x32_bf16 v[92:95], v[150:153], v[116:119], v[92:95]
	v_mfma_f32_16x16x32_bf16 v[88:91], v[150:153], v[186:189], v[88:91]
	v_mfma_f32_16x16x32_bf16 v[84:87], v[158:161], v[116:119], v[84:87]
	v_mfma_f32_16x16x32_bf16 v[80:83], v[158:161], v[186:189], v[80:83]
	v_mfma_f32_16x16x32_bf16 v[76:79], v[166:169], v[116:119], v[76:79]
	v_mfma_f32_16x16x32_bf16 v[72:75], v[166:169], v[186:189], v[72:75]
	v_mfma_f32_16x16x32_bf16 v[68:71], v[174:177], v[116:119], v[68:71]
	v_mfma_f32_16x16x32_bf16 v[64:67], v[174:177], v[186:189], v[64:67]
	v_mfma_f32_16x16x32_bf16 v[92:95], v[154:157], v[182:185], v[92:95]
	v_mfma_f32_16x16x32_bf16 v[88:91], v[154:157], v[196:199], v[88:91]
	v_mfma_f32_16x16x32_bf16 v[84:87], v[162:165], v[182:185], v[84:87]
	v_mfma_f32_16x16x32_bf16 v[80:83], v[162:165], v[196:199], v[80:83]
	v_mfma_f32_16x16x32_bf16 v[76:79], v[170:173], v[182:185], v[76:79]
	v_mfma_f32_16x16x32_bf16 v[72:75], v[170:173], v[196:199], v[72:75]
	v_mfma_f32_16x16x32_bf16 v[68:71], v[178:181], v[182:185], v[68:71]
	v_mfma_f32_16x16x32_bf16 v[64:67], v[178:181], v[196:199], v[64:67]
	s_barrier
	ds_read_b128 v[150:153], v144 offset:16384
	ds_read_b128 v[154:157], v144 offset:17408
	ds_read_b128 v[158:161], v144 offset:18432
	ds_read_b128 v[162:165], v144 offset:19456
	ds_read_b128 v[166:169], v144 offset:20480
	ds_read_b128 v[170:173], v144 offset:21504
	ds_read_b128 v[174:177], v144 offset:22528
	ds_read_b128 v[178:181], v144 offset:23552
	s_waitcnt vmcnt(4)
	s_barrier
	s_waitcnt lgkmcnt(0)
	s_waitcnt lgkmcnt(0)
	v_mfma_f32_16x16x32_bf16 v[60:63], v[150:153], v[128:131], v[60:63]
	v_mfma_f32_16x16x32_bf16 v[56:59], v[150:153], v[136:139], v[56:59]
	v_mfma_f32_16x16x32_bf16 v[52:55], v[158:161], v[128:131], v[52:55]
	v_mfma_f32_16x16x32_bf16 v[48:51], v[158:161], v[136:139], v[48:51]
	v_mfma_f32_16x16x32_bf16 v[44:47], v[166:169], v[128:131], v[44:47]
	v_mfma_f32_16x16x32_bf16 v[40:43], v[166:169], v[136:139], v[40:43]
	v_mfma_f32_16x16x32_bf16 v[36:39], v[174:177], v[128:131], v[36:39]
	v_mfma_f32_16x16x32_bf16 v[32:35], v[174:177], v[136:139], v[32:35]
	v_mfma_f32_16x16x32_bf16 v[60:63], v[154:157], v[132:135], v[60:63]
	v_mfma_f32_16x16x32_bf16 v[56:59], v[154:157], v[146:149], v[56:59]
	v_mfma_f32_16x16x32_bf16 v[52:55], v[162:165], v[132:135], v[52:55]
	v_mfma_f32_16x16x32_bf16 v[48:51], v[162:165], v[146:149], v[48:51]
	v_mfma_f32_16x16x32_bf16 v[44:47], v[170:173], v[132:135], v[44:47]
	v_mfma_f32_16x16x32_bf16 v[40:43], v[170:173], v[146:149], v[40:43]
	v_mfma_f32_16x16x32_bf16 v[36:39], v[178:181], v[132:135], v[36:39]
	v_mfma_f32_16x16x32_bf16 v[32:35], v[178:181], v[146:149], v[32:35]
	v_mfma_f32_16x16x32_bf16 v[28:31], v[150:153], v[116:119], v[28:31]
	v_mfma_f32_16x16x32_bf16 v[24:27], v[150:153], v[186:189], v[24:27]
	v_mfma_f32_16x16x32_bf16 v[20:23], v[158:161], v[116:119], v[20:23]
	v_mfma_f32_16x16x32_bf16 v[16:19], v[158:161], v[186:189], v[16:19]
	v_mfma_f32_16x16x32_bf16 v[12:15], v[166:169], v[116:119], v[12:15]
	v_mfma_f32_16x16x32_bf16 v[8:11], v[166:169], v[186:189], v[8:11]
	v_mfma_f32_16x16x32_bf16 v[4:7], v[174:177], v[116:119], v[4:7]
	v_mfma_f32_16x16x32_bf16 v[0:3], v[174:177], v[186:189], v[0:3]
	v_mfma_f32_16x16x32_bf16 v[200:203], v[154:157], v[182:185], v[28:31]
	v_mfma_f32_16x16x32_bf16 v[204:207], v[154:157], v[196:199], v[24:27]
	v_mfma_f32_16x16x32_bf16 v[208:211], v[162:165], v[182:185], v[20:23]
	v_mfma_f32_16x16x32_bf16 v[212:215], v[162:165], v[196:199], v[16:19]
	v_mfma_f32_16x16x32_bf16 v[216:219], v[170:173], v[182:185], v[12:15]
	v_mfma_f32_16x16x32_bf16 v[220:223], v[170:173], v[196:199], v[8:11]
	v_mfma_f32_16x16x32_bf16 v[224:227], v[178:181], v[182:185], v[4:7]
	v_mfma_f32_16x16x32_bf16 v[184:187], v[178:181], v[196:199], v[0:3]
	s_nop 1
	v_add_u32_e32 v0, 0x18000, v195
	s_barrier
	ds_read_b128 v[24:27], v0
	ds_read_b128 v[28:31], v0 offset:1024
	ds_read_b128 v[188:191], v0 offset:2048
	ds_read_b128 v[196:199], v0 offset:3072
	ds_read_b128 v[0:3], v144 offset:32768
	ds_read_b128 v[4:7], v144 offset:33792
	ds_read_b128 v[8:11], v144 offset:34816
	ds_read_b128 v[12:15], v144 offset:35840
	ds_read_b128 v[16:19], v144 offset:36864
	ds_read_b128 v[20:23], v144 offset:37888
	ds_read_b128 v[176:179], v144 offset:38912
	ds_read_b128 v[228:231], v144 offset:39936
	s_waitcnt vmcnt(2)
	s_barrier
	s_waitcnt lgkmcnt(0)
	s_waitcnt lgkmcnt(0)
	v_mfma_f32_16x16x32_bf16 v[116:119], v[0:3], v[24:27], v[124:127]
	v_mfma_f32_16x16x32_bf16 v[148:151], v[4:7], v[28:31], v[116:119]
	v_mfma_f32_16x16x32_bf16 v[116:119], v[0:3], v[188:191], v[120:123]
	v_mfma_f32_16x16x32_bf16 v[120:123], v[8:11], v[24:27], v[140:143]
	v_mfma_f32_16x16x32_bf16 v[112:115], v[8:11], v[188:191], v[112:115]
	v_mfma_f32_16x16x32_bf16 v[108:111], v[16:19], v[24:27], v[108:111]
	v_mfma_f32_16x16x32_bf16 v[104:107], v[16:19], v[188:191], v[104:107]
	v_mfma_f32_16x16x32_bf16 v[100:103], v[176:179], v[24:27], v[100:103]
	v_mfma_f32_16x16x32_bf16 v[96:99], v[176:179], v[188:191], v[96:99]
	v_mfma_f32_16x16x32_bf16 v[116:119], v[4:7], v[196:199], v[116:119]
	v_mfma_f32_16x16x32_bf16 v[120:123], v[12:15], v[28:31], v[120:123]
	v_mfma_f32_16x16x32_bf16 v[124:127], v[12:15], v[196:199], v[112:115]
	v_mfma_f32_16x16x32_bf16 v[128:131], v[20:23], v[28:31], v[108:111]
	v_mfma_f32_16x16x32_bf16 v[132:135], v[20:23], v[196:199], v[104:107]
	v_mfma_f32_16x16x32_bf16 v[136:139], v[228:231], v[28:31], v[100:103]
	v_mfma_f32_16x16x32_bf16 v[140:143], v[228:231], v[196:199], v[96:99]
	v_add_u32_e32 v108, 0x1c000, v195
	s_barrier
	ds_read_b128 v[96:99], v108
	ds_read_b128 v[100:103], v108 offset:1024
	ds_read_b128 v[104:107], v108 offset:2048
	ds_read_b128 v[108:111], v108 offset:3072
	s_waitcnt vmcnt(0)
	s_barrier
	s_waitcnt lgkmcnt(0)
	s_waitcnt lgkmcnt(0)
	v_mfma_f32_16x16x32_bf16 v[92:95], v[0:3], v[96:99], v[92:95]
	v_mfma_f32_16x16x32_bf16 v[0:3], v[0:3], v[104:107], v[88:91]
	v_mfma_f32_16x16x32_bf16 v[152:155], v[4:7], v[108:111], v[0:3]
	v_mfma_f32_16x16x32_bf16 v[0:3], v[8:11], v[96:99], v[84:87]
	v_mfma_f32_16x16x32_bf16 v[156:159], v[12:15], v[100:103], v[0:3]
	v_mfma_f32_16x16x32_bf16 v[0:3], v[8:11], v[104:107], v[80:83]
	v_mfma_f32_16x16x32_bf16 v[160:163], v[12:15], v[108:111], v[0:3]
	v_mfma_f32_16x16x32_bf16 v[0:3], v[16:19], v[96:99], v[76:79]
	v_mfma_f32_16x16x32_bf16 v[164:167], v[20:23], v[100:103], v[0:3]
	v_mfma_f32_16x16x32_bf16 v[0:3], v[16:19], v[104:107], v[72:75]
	v_mfma_f32_16x16x32_bf16 v[168:171], v[20:23], v[108:111], v[0:3]
	v_mfma_f32_16x16x32_bf16 v[0:3], v[176:179], v[96:99], v[68:71]
	v_mfma_f32_16x16x32_bf16 v[172:175], v[228:231], v[100:103], v[0:3]
	v_mfma_f32_16x16x32_bf16 v[0:3], v[176:179], v[104:107], v[64:67]
	v_mfma_f32_16x16x32_bf16 v[180:183], v[4:7], v[100:103], v[92:95]
	v_mfma_f32_16x16x32_bf16 v[176:179], v[228:231], v[108:111], v[0:3]
	s_barrier
	ds_read_b128 v[64:67], v144 offset:49152
	ds_read_b128 v[68:71], v144 offset:50176
	ds_read_b128 v[72:75], v144 offset:51200
	ds_read_b128 v[76:79], v144 offset:52224
	ds_read_b128 v[80:83], v144 offset:53248
	ds_read_b128 v[84:87], v144 offset:54272
	ds_read_b128 v[88:91], v144 offset:55296
	ds_read_b128 v[92:95], v144 offset:56320
	s_barrier
	s_waitcnt lgkmcnt(0)
	s_waitcnt lgkmcnt(0)
	v_mfma_f32_16x16x32_bf16 v[0:3], v[64:67], v[24:27], v[60:63]
	v_mfma_f32_16x16x32_bf16 v[8:11], v[72:75], v[24:27], v[52:55]
	v_mfma_f32_16x16x32_bf16 v[16:19], v[80:83], v[24:27], v[44:47]
	v_mfma_f32_16x16x32_bf16 v[24:27], v[88:91], v[24:27], v[36:39]
	v_mfma_f32_16x16x32_bf16 v[0:3], v[68:71], v[28:31], v[0:3]
	v_mfma_f32_16x16x32_bf16 v[4:7], v[64:67], v[188:191], v[56:59]
	v_mfma_f32_16x16x32_bf16 v[8:11], v[76:79], v[28:31], v[8:11]
	v_mfma_f32_16x16x32_bf16 v[12:15], v[72:75], v[188:191], v[48:51]
	v_mfma_f32_16x16x32_bf16 v[16:19], v[84:87], v[28:31], v[16:19]
	v_mfma_f32_16x16x32_bf16 v[20:23], v[80:83], v[188:191], v[40:43]
	v_mfma_f32_16x16x32_bf16 v[24:27], v[92:95], v[28:31], v[24:27]
	v_mfma_f32_16x16x32_bf16 v[28:31], v[88:91], v[188:191], v[32:35]
	v_mfma_f32_16x16x32_bf16 v[4:7], v[68:71], v[196:199], v[4:7]
	v_mfma_f32_16x16x32_bf16 v[12:15], v[76:79], v[196:199], v[12:15]
	v_mfma_f32_16x16x32_bf16 v[20:23], v[84:87], v[196:199], v[20:23]
	v_mfma_f32_16x16x32_bf16 v[28:31], v[92:95], v[196:199], v[28:31]
	v_mfma_f32_16x16x32_bf16 v[32:35], v[64:67], v[96:99], v[200:203]
	v_mfma_f32_16x16x32_bf16 v[36:39], v[64:67], v[104:107], v[204:207]
	v_mfma_f32_16x16x32_bf16 v[40:43], v[72:75], v[96:99], v[208:211]
	v_mfma_f32_16x16x32_bf16 v[44:47], v[72:75], v[104:107], v[212:215]
	v_mfma_f32_16x16x32_bf16 v[48:51], v[80:83], v[96:99], v[216:219]
	v_mfma_f32_16x16x32_bf16 v[52:55], v[80:83], v[104:107], v[220:223]
	v_mfma_f32_16x16x32_bf16 v[56:59], v[88:91], v[96:99], v[224:227]
	v_mfma_f32_16x16x32_bf16 v[60:63], v[88:91], v[104:107], v[184:187]
	v_mfma_f32_16x16x32_bf16 v[32:35], v[68:71], v[100:103], v[32:35]
	v_mfma_f32_16x16x32_bf16 v[36:39], v[68:71], v[108:111], v[36:39]
	v_mfma_f32_16x16x32_bf16 v[40:43], v[76:79], v[100:103], v[40:43]
	v_mfma_f32_16x16x32_bf16 v[44:47], v[76:79], v[108:111], v[44:47]
	v_mfma_f32_16x16x32_bf16 v[48:51], v[84:87], v[100:103], v[48:51]
	v_mfma_f32_16x16x32_bf16 v[52:55], v[84:87], v[108:111], v[52:55]
	v_mfma_f32_16x16x32_bf16 v[56:59], v[92:95], v[100:103], v[56:59]
	v_mfma_f32_16x16x32_bf16 v[60:63], v[92:95], v[108:111], v[60:63]
	s_cmpk_gt_u32 s52, 0xff
	s_barrier
	s_cbranch_scc1 .LBB0_826
	s_barrier
	s_branch .LBB0_826

.LBB0_1019:
	v_and_b32_e32 v2, 15, v1
	v_and_b32_e32 v3, 48, v1
	v_lshlrev_b32_e32 v2, 6, v2
	v_lshlrev_b32_e32 v1, 2, v1
	v_or_b32_e32 v4, v2, v3
	v_and_b32_e32 v1, 32, v1
	s_lshl_b32 s3, s48, 13
	v_bitop3_b32 v4, v4, s3, v1 bitop3:0xde
	s_lshl_b32 s3, s53, 6
	s_and_b32 s3, s3, 0x3000
	v_bitop3_b32 v2, v2, v1, v3 bitop3:0x36
	s_add_u32 s48, s38, 0x80
	v_add_u32_e32 v137, s93, v0
	v_or_b32_e32 v136, s3, v2
	s_addc_u32 s49, s39, 0
	v_readfirstlane_b32 s3, v137
	v_add_u32_e32 v138, 0x2000, v137
	v_lshl_add_u64 v[2:3], s[48:49], 0, v[192:193]
	s_mov_b32 m0, s3
	v_readfirstlane_b32 s3, v138
	s_add_u32 s48, s40, 0x80
	v_add_u32_e32 v139, 0x8000, v130
	s_waitcnt vmcnt(4)
	s_barrier
	global_load_lds_dwordx4 v[2:3], off
	v_lshl_add_u64 v[2:3], v[2:3], 0, s[34:35]
	s_mov_b32 m0, s3
	s_addc_u32 s49, s41, 0
	v_readfirstlane_b32 s3, v139
	v_add_u32_e32 v140, 0xa000, v130
	global_load_lds_dwordx4 v[2:3], off
	v_lshl_add_u64 v[2:3], s[48:49], 0, v[192:193]
	s_mov_b32 m0, s3
	v_readfirstlane_b32 s3, v140
	s_add_u32 s48, s44, 0x80
	v_add_u32_e32 v141, s89, v0
	global_load_lds_dwordx4 v[2:3], off
	v_lshl_add_u64 v[2:3], v[2:3], 0, s[34:35]
	s_mov_b32 m0, s3
	s_addc_u32 s49, s45, 0
	v_readfirstlane_b32 s3, v141
	v_add_u32_e32 v142, 0x2000, v141
	global_load_lds_dwordx4 v[2:3], off
	v_lshl_add_u64 v[2:3], s[48:49], 0, v[192:193]
	s_mov_b32 m0, s3
	v_readfirstlane_b32 s3, v142
	global_load_lds_dwordx4 v[2:3], off
	v_lshl_add_u64 v[0:1], v[2:3], 0, s[34:35]
	s_mov_b32 m0, s3
	s_mov_b32 s3, -2
	global_load_lds_dwordx4 v[0:1], off
	s_waitcnt vmcnt(6)
	v_mov_b32_e32 v0, 0
	s_mov_b64 s[48:49], 0
	v_add_u32_e32 v195, 0, v4
	v_mov_b32_e32 v1, v0
	v_mov_b32_e32 v2, v0
	v_mov_b32_e32 v3, v0
	v_mov_b32_e32 v4, v0
	v_mov_b32_e32 v5, v0
	v_mov_b32_e32 v6, v0
	v_mov_b32_e32 v7, v0
	v_mov_b32_e32 v8, v0
	v_mov_b32_e32 v9, v0
	v_mov_b32_e32 v10, v0
	v_mov_b32_e32 v11, v0
	v_mov_b32_e32 v12, v0
	v_mov_b32_e32 v13, v0
	v_mov_b32_e32 v14, v0
	v_mov_b32_e32 v15, v0
	v_mov_b32_e32 v16, v0
	v_mov_b32_e32 v17, v0
	v_mov_b32_e32 v18, v0
	v_mov_b32_e32 v19, v0
	v_mov_b32_e32 v20, v0
	v_mov_b32_e32 v21, v0
	v_mov_b32_e32 v22, v0
	v_mov_b32_e32 v23, v0
	v_mov_b32_e32 v24, v0
	v_mov_b32_e32 v25, v0
	v_mov_b32_e32 v26, v0
	v_mov_b32_e32 v27, v0
	v_mov_b32_e32 v28, v0
	v_mov_b32_e32 v29, v0
	v_mov_b32_e32 v30, v0
	v_mov_b32_e32 v31, v0
	v_mov_b32_e32 v32, v0
	v_mov_b32_e32 v33, v0
	v_mov_b32_e32 v34, v0
	v_mov_b32_e32 v35, v0
	v_mov_b32_e32 v36, v0
	v_mov_b32_e32 v37, v0
	v_mov_b32_e32 v38, v0
	v_mov_b32_e32 v39, v0
	v_mov_b32_e32 v40, v0
	v_mov_b32_e32 v41, v0
	v_mov_b32_e32 v42, v0
	v_mov_b32_e32 v43, v0
	v_mov_b32_e32 v44, v0
	v_mov_b32_e32 v45, v0
	v_mov_b32_e32 v46, v0
	v_mov_b32_e32 v47, v0
	v_mov_b32_e32 v48, v0
	v_mov_b32_e32 v49, v0
	v_mov_b32_e32 v50, v0
	v_mov_b32_e32 v51, v0
	v_mov_b32_e32 v52, v0
	v_mov_b32_e32 v53, v0
	v_mov_b32_e32 v54, v0
	v_mov_b32_e32 v55, v0
	v_mov_b32_e32 v56, v0
	v_mov_b32_e32 v57, v0
	v_mov_b32_e32 v58, v0
	v_mov_b32_e32 v59, v0
	v_mov_b32_e32 v60, v0
	v_mov_b32_e32 v61, v0
	v_mov_b32_e32 v62, v0
	v_mov_b32_e32 v63, v0
	v_mov_b32_e32 v64, v0
	v_mov_b32_e32 v65, v0
	v_mov_b32_e32 v66, v0
	v_mov_b32_e32 v67, v0
	v_mov_b32_e32 v68, v0
	v_mov_b32_e32 v69, v0
	v_mov_b32_e32 v70, v0
	v_mov_b32_e32 v71, v0
	v_mov_b32_e32 v72, v0
	v_mov_b32_e32 v73, v0
	v_mov_b32_e32 v74, v0
	v_mov_b32_e32 v75, v0
	v_mov_b32_e32 v76, v0
	v_mov_b32_e32 v77, v0
	v_mov_b32_e32 v78, v0
	v_mov_b32_e32 v79, v0
	v_mov_b32_e32 v80, v0
	v_mov_b32_e32 v81, v0
	v_mov_b32_e32 v82, v0
	v_mov_b32_e32 v83, v0
	v_mov_b32_e32 v84, v0
	v_mov_b32_e32 v85, v0
	v_mov_b32_e32 v86, v0
	v_mov_b32_e32 v87, v0
	v_mov_b32_e32 v88, v0
	v_mov_b32_e32 v89, v0
	v_mov_b32_e32 v90, v0
	v_mov_b32_e32 v91, v0
	v_mov_b32_e32 v92, v0
	v_mov_b32_e32 v93, v0
	v_mov_b32_e32 v94, v0
	v_mov_b32_e32 v95, v0
	v_mov_b32_e32 v96, v0
	v_mov_b32_e32 v97, v0
	v_mov_b32_e32 v98, v0
	v_mov_b32_e32 v99, v0
	v_mov_b32_e32 v100, v0
	v_mov_b32_e32 v101, v0
	v_mov_b32_e32 v102, v0
	v_mov_b32_e32 v103, v0
	v_mov_b32_e32 v104, v0
	v_mov_b32_e32 v105, v0
	v_mov_b32_e32 v106, v0
	v_mov_b32_e32 v107, v0
	v_mov_b32_e32 v108, v0
	v_mov_b32_e32 v109, v0
	v_mov_b32_e32 v110, v0
	v_mov_b32_e32 v111, v0
	v_mov_b32_e32 v112, v0
	v_mov_b32_e32 v113, v0
	v_mov_b32_e32 v114, v0
	v_mov_b32_e32 v115, v0
	v_mov_b32_e32 v116, v0
	v_mov_b32_e32 v117, v0
	v_mov_b32_e32 v118, v0
	v_mov_b32_e32 v119, v0
	v_mov_b32_e32 v120, v0
	v_mov_b32_e32 v121, v0
	v_mov_b32_e32 v122, v0
	v_mov_b32_e32 v123, v0
	v_mov_b32_e32 v124, v0
	v_mov_b32_e32 v125, v0
	v_mov_b32_e32 v126, v0
	v_mov_b32_e32 v127, v0
	v_readfirstlane_b32 s14, v130
	s_barrier
.LBB0_1020:
	v_add_u32_e32 v143, s77, v136
	ds_read_b128 v[146:149], v143
	ds_read_b128 v[150:153], v143 offset:1024
	ds_read_b128 v[154:157], v143 offset:2048
	ds_read_b128 v[158:161], v143 offset:3072
	s_add_u32 s13, s46, s48
	s_addc_u32 s72, s47, s49
	s_add_u32 s54, s13, 0x80
	s_addc_u32 s55, s72, 0
	v_add_u32_e32 v143, 0xc000, v130
	s_add_i32 m0, s14, 0xc000
	ds_read_b128 v[162:165], v195
	ds_read_b128 v[166:169], v195 offset:1024
	ds_read_b128 v[170:173], v195 offset:2048
	ds_read_b128 v[174:177], v195 offset:3072
	ds_read_b128 v[178:181], v195 offset:4096
	ds_read_b128 v[182:185], v195 offset:5120
	ds_read_b128 v[186:189], v195 offset:6144
	ds_read_b128 v[196:199], v195 offset:7168
	global_load_lds_dwordx4 v192, s[54:55]
	s_add_u32 s10, s54, s34
	s_addc_u32 s11, s55, s35
	v_add_u32_e32 v144, 0xe000, v130
	s_nop 0
	s_add_i32 m0, s14, 0xe000
	s_nop 0
	global_load_lds_dwordx4 v192, s[10:11]
	s_waitcnt lgkmcnt(8)
	s_barrier
	s_waitcnt lgkmcnt(0)
	s_waitcnt lgkmcnt(0)
	v_mfma_f32_16x16x32_bf16 v[124:127], v[162:165], v[146:149], v[124:127]
	v_mfma_f32_16x16x32_bf16 v[120:123], v[162:165], v[154:157], v[120:123]
	v_mfma_f32_16x16x32_bf16 v[116:119], v[170:173], v[146:149], v[116:119]
	v_mfma_f32_16x16x32_bf16 v[112:115], v[170:173], v[154:157], v[112:115]
	v_mfma_f32_16x16x32_bf16 v[108:111], v[178:181], v[146:149], v[108:111]
	v_mfma_f32_16x16x32_bf16 v[104:107], v[178:181], v[154:157], v[104:107]
	v_mfma_f32_16x16x32_bf16 v[100:103], v[186:189], v[146:149], v[100:103]
	v_mfma_f32_16x16x32_bf16 v[96:99], v[186:189], v[154:157], v[96:99]
	v_mfma_f32_16x16x32_bf16 v[124:127], v[166:169], v[150:153], v[124:127]
	v_mfma_f32_16x16x32_bf16 v[120:123], v[166:169], v[158:161], v[120:123]
	v_mfma_f32_16x16x32_bf16 v[116:119], v[174:177], v[150:153], v[116:119]
	v_mfma_f32_16x16x32_bf16 v[112:115], v[174:177], v[158:161], v[112:115]
	v_mfma_f32_16x16x32_bf16 v[108:111], v[182:185], v[150:153], v[108:111]
	v_mfma_f32_16x16x32_bf16 v[104:107], v[182:185], v[158:161], v[104:107]
	v_mfma_f32_16x16x32_bf16 v[100:103], v[196:199], v[150:153], v[100:103]
	v_mfma_f32_16x16x32_bf16 v[96:99], v[196:199], v[158:161], v[96:99]
	s_barrier
	s_add_u32 s73, s38, s48
	s_addc_u32 s74, s39, s49
	s_add_u32 s54, s73, 0x100
	s_addc_u32 s55, s74, 0
	v_add_u32_e32 v145, s33, v136
	s_add_i32 m0, s14, s77
	ds_read_b128 v[200:203], v145
	ds_read_b128 v[204:207], v145 offset:1024
	ds_read_b128 v[208:211], v145 offset:2048
	ds_read_b128 v[212:215], v145 offset:3072
	global_load_lds_dwordx4 v192, s[54:55]
	s_add_u32 s10, s54, s34
	s_addc_u32 s11, s55, s35
	s_add_i32 m0, s14, s77
	s_add_i32 m0, m0, 0x2000
	s_nop 0
	global_load_lds_dwordx4 v192, s[10:11]
	s_barrier
	s_waitcnt lgkmcnt(0)
	s_waitcnt lgkmcnt(0)
	v_mfma_f32_16x16x32_bf16 v[92:95], v[162:165], v[200:203], v[92:95]
	v_mfma_f32_16x16x32_bf16 v[88:91], v[162:165], v[208:211], v[88:91]
	v_mfma_f32_16x16x32_bf16 v[84:87], v[170:173], v[200:203], v[84:87]
	v_mfma_f32_16x16x32_bf16 v[80:83], v[170:173], v[208:211], v[80:83]
	v_mfma_f32_16x16x32_bf16 v[76:79], v[178:181], v[200:203], v[76:79]
	v_mfma_f32_16x16x32_bf16 v[72:75], v[178:181], v[208:211], v[72:75]
	v_mfma_f32_16x16x32_bf16 v[68:71], v[186:189], v[200:203], v[68:71]
	v_mfma_f32_16x16x32_bf16 v[64:67], v[186:189], v[208:211], v[64:67]
	v_mfma_f32_16x16x32_bf16 v[92:95], v[166:169], v[204:207], v[92:95]
	v_mfma_f32_16x16x32_bf16 v[88:91], v[166:169], v[212:215], v[88:91]
	v_mfma_f32_16x16x32_bf16 v[84:87], v[174:177], v[204:207], v[84:87]
	v_mfma_f32_16x16x32_bf16 v[80:83], v[174:177], v[212:215], v[80:83]
	v_mfma_f32_16x16x32_bf16 v[76:79], v[182:185], v[204:207], v[76:79]
	v_mfma_f32_16x16x32_bf16 v[72:75], v[182:185], v[212:215], v[72:75]
	v_mfma_f32_16x16x32_bf16 v[68:71], v[196:199], v[204:207], v[68:71]
	v_mfma_f32_16x16x32_bf16 v[64:67], v[196:199], v[212:215], v[64:67]
	s_add_u32 s75, s40, s48
	s_addc_u32 s78, s41, s49
	s_add_u32 s54, s75, 0x100
	s_addc_u32 s55, s78, 0
	s_mov_b32 m0, s14
	s_barrier
	ds_read_b128 v[162:165], v195 offset:16384
	ds_read_b128 v[166:169], v195 offset:17408
	ds_read_b128 v[170:173], v195 offset:18432
	ds_read_b128 v[174:177], v195 offset:19456
	ds_read_b128 v[178:181], v195 offset:20480
	ds_read_b128 v[182:185], v195 offset:21504
	ds_read_b128 v[186:189], v195 offset:22528
	ds_read_b128 v[196:199], v195 offset:23552
	global_load_lds_dwordx4 v192, s[54:55]
	s_add_u32 s10, s54, s34
	s_addc_u32 s11, s55, s35
	s_add_i32 m0, s14, 0x2000
	s_nop 0
	global_load_lds_dwordx4 v192, s[10:11]
	s_barrier
	s_waitcnt lgkmcnt(0)
	s_waitcnt lgkmcnt(0)
	v_mfma_f32_16x16x32_bf16 v[60:63], v[162:165], v[146:149], v[60:63]
	v_mfma_f32_16x16x32_bf16 v[56:59], v[162:165], v[154:157], v[56:59]
	v_mfma_f32_16x16x32_bf16 v[52:55], v[170:173], v[146:149], v[52:55]
	v_mfma_f32_16x16x32_bf16 v[48:51], v[170:173], v[154:157], v[48:51]
	v_mfma_f32_16x16x32_bf16 v[44:47], v[178:181], v[146:149], v[44:47]
	v_mfma_f32_16x16x32_bf16 v[40:43], v[178:181], v[154:157], v[40:43]
	v_mfma_f32_16x16x32_bf16 v[36:39], v[186:189], v[146:149], v[36:39]
	v_mfma_f32_16x16x32_bf16 v[32:35], v[186:189], v[154:157], v[32:35]
	v_mfma_f32_16x16x32_bf16 v[60:63], v[166:169], v[150:153], v[60:63]
	v_mfma_f32_16x16x32_bf16 v[56:59], v[166:169], v[158:161], v[56:59]
	v_mfma_f32_16x16x32_bf16 v[52:55], v[174:177], v[150:153], v[52:55]
	v_mfma_f32_16x16x32_bf16 v[48:51], v[174:177], v[158:161], v[48:51]
	v_mfma_f32_16x16x32_bf16 v[44:47], v[182:185], v[150:153], v[44:47]
	v_mfma_f32_16x16x32_bf16 v[40:43], v[182:185], v[158:161], v[40:43]
	v_mfma_f32_16x16x32_bf16 v[36:39], v[196:199], v[150:153], v[36:39]
	v_mfma_f32_16x16x32_bf16 v[32:35], v[196:199], v[158:161], v[32:35]
	s_barrier
	s_add_u32 s79, s44, s48
	s_addc_u32 s80, s45, s49
	s_add_u32 s54, s79, 0x100
	s_addc_u32 s55, s80, 0
	s_add_i32 m0, s14, s33
	s_nop 0
	global_load_lds_dwordx4 v192, s[54:55]
	s_add_u32 s10, s54, s34
	s_addc_u32 s11, s55, s35
	s_add_i32 m0, s14, s33
	s_add_i32 m0, m0, 0x2000
	s_nop 0
	global_load_lds_dwordx4 v192, s[10:11]
	s_waitcnt vmcnt(6)
	s_barrier
	v_mfma_f32_16x16x32_bf16 v[28:31], v[162:165], v[200:203], v[28:31]
	v_mfma_f32_16x16x32_bf16 v[24:27], v[162:165], v[208:211], v[24:27]
	v_mfma_f32_16x16x32_bf16 v[20:23], v[170:173], v[200:203], v[20:23]
	v_mfma_f32_16x16x32_bf16 v[16:19], v[170:173], v[208:211], v[16:19]
	v_mfma_f32_16x16x32_bf16 v[12:15], v[178:181], v[200:203], v[12:15]
	v_mfma_f32_16x16x32_bf16 v[8:11], v[178:181], v[208:211], v[8:11]
	v_mfma_f32_16x16x32_bf16 v[4:7], v[186:189], v[200:203], v[4:7]
	v_mfma_f32_16x16x32_bf16 v[0:3], v[186:189], v[208:211], v[0:3]
	v_mfma_f32_16x16x32_bf16 v[28:31], v[166:169], v[204:207], v[28:31]
	v_mfma_f32_16x16x32_bf16 v[24:27], v[166:169], v[212:215], v[24:27]
	v_mfma_f32_16x16x32_bf16 v[20:23], v[174:177], v[204:207], v[20:23]
	v_mfma_f32_16x16x32_bf16 v[16:19], v[174:177], v[212:215], v[16:19]
	v_mfma_f32_16x16x32_bf16 v[12:15], v[182:185], v[204:207], v[12:15]
	v_mfma_f32_16x16x32_bf16 v[8:11], v[182:185], v[212:215], v[8:11]
	v_mfma_f32_16x16x32_bf16 v[4:7], v[196:199], v[204:207], v[4:7]
	v_mfma_f32_16x16x32_bf16 v[0:3], v[196:199], v[212:215], v[0:3]
	v_add_u32_e32 v145, s93, v136
	s_barrier
	ds_read_b128 v[146:149], v145
	ds_read_b128 v[150:153], v145 offset:1024
	ds_read_b128 v[154:157], v145 offset:2048
	ds_read_b128 v[158:161], v145 offset:3072
	s_add_u32 s54, s13, 0x100
	s_addc_u32 s55, s72, 0
	s_add_i32 m0, s14, 0x4000
	ds_read_b128 v[162:165], v195 offset:32768
	ds_read_b128 v[166:169], v195 offset:33792
	ds_read_b128 v[170:173], v195 offset:34816
	ds_read_b128 v[174:177], v195 offset:35840
	ds_read_b128 v[178:181], v195 offset:36864
	ds_read_b128 v[182:185], v195 offset:37888
	ds_read_b128 v[186:189], v195 offset:38912
	ds_read_b128 v[196:199], v195 offset:39936
	global_load_lds_dwordx4 v192, s[54:55]
	s_add_u32 s10, s54, s34
	s_addc_u32 s11, s55, s35
	s_add_i32 m0, s14, 0x6000
	s_nop 0
	global_load_lds_dwordx4 v192, s[10:11]
	s_waitcnt lgkmcnt(8)
	s_barrier
	s_waitcnt lgkmcnt(0)
	s_waitcnt lgkmcnt(0)
	v_mfma_f32_16x16x32_bf16 v[124:127], v[162:165], v[146:149], v[124:127]
	v_mfma_f32_16x16x32_bf16 v[120:123], v[162:165], v[154:157], v[120:123]
	v_mfma_f32_16x16x32_bf16 v[116:119], v[170:173], v[146:149], v[116:119]
	v_mfma_f32_16x16x32_bf16 v[112:115], v[170:173], v[154:157], v[112:115]
	v_mfma_f32_16x16x32_bf16 v[108:111], v[178:181], v[146:149], v[108:111]
	v_mfma_f32_16x16x32_bf16 v[104:107], v[178:181], v[154:157], v[104:107]
	v_mfma_f32_16x16x32_bf16 v[100:103], v[186:189], v[146:149], v[100:103]
	v_mfma_f32_16x16x32_bf16 v[96:99], v[186:189], v[154:157], v[96:99]
	v_mfma_f32_16x16x32_bf16 v[124:127], v[166:169], v[150:153], v[124:127]
	v_mfma_f32_16x16x32_bf16 v[120:123], v[166:169], v[158:161], v[120:123]
	v_mfma_f32_16x16x32_bf16 v[116:119], v[174:177], v[150:153], v[116:119]
	v_mfma_f32_16x16x32_bf16 v[112:115], v[174:177], v[158:161], v[112:115]
	v_mfma_f32_16x16x32_bf16 v[108:111], v[182:185], v[150:153], v[108:111]
	v_mfma_f32_16x16x32_bf16 v[104:107], v[182:185], v[158:161], v[104:107]
	v_mfma_f32_16x16x32_bf16 v[100:103], v[196:199], v[150:153], v[100:103]
	v_mfma_f32_16x16x32_bf16 v[96:99], v[196:199], v[158:161], v[96:99]
	s_barrier
	s_add_u32 s54, s73, 0x180
	s_addc_u32 s55, s74, 0
	v_add_u32_e32 v145, s89, v136
	s_add_i32 m0, s14, s93
	ds_read_b128 v[200:203], v145
	ds_read_b128 v[204:207], v145 offset:1024
	ds_read_b128 v[208:211], v145 offset:2048
	ds_read_b128 v[212:215], v145 offset:3072
	global_load_lds_dwordx4 v192, s[54:55]
	s_add_u32 s10, s54, s34
	s_addc_u32 s11, s55, s35
	s_add_i32 m0, s14, s93
	s_add_i32 m0, m0, 0x2000
	s_nop 0
	global_load_lds_dwordx4 v192, s[10:11]
	s_barrier
	s_waitcnt lgkmcnt(0)
	s_waitcnt lgkmcnt(0)
	v_mfma_f32_16x16x32_bf16 v[92:95], v[162:165], v[200:203], v[92:95]
	v_mfma_f32_16x16x32_bf16 v[88:91], v[162:165], v[208:211], v[88:91]
	v_mfma_f32_16x16x32_bf16 v[84:87], v[170:173], v[200:203], v[84:87]
	v_mfma_f32_16x16x32_bf16 v[80:83], v[170:173], v[208:211], v[80:83]
	v_mfma_f32_16x16x32_bf16 v[76:79], v[178:181], v[200:203], v[76:79]
	v_mfma_f32_16x16x32_bf16 v[72:75], v[178:181], v[208:211], v[72:75]
	v_mfma_f32_16x16x32_bf16 v[68:71], v[186:189], v[200:203], v[68:71]
	v_mfma_f32_16x16x32_bf16 v[64:67], v[186:189], v[208:211], v[64:67]
	v_mfma_f32_16x16x32_bf16 v[92:95], v[166:169], v[204:207], v[92:95]
	v_mfma_f32_16x16x32_bf16 v[88:91], v[166:169], v[212:215], v[88:91]
	v_mfma_f32_16x16x32_bf16 v[84:87], v[174:177], v[204:207], v[84:87]
	v_mfma_f32_16x16x32_bf16 v[80:83], v[174:177], v[212:215], v[80:83]
	v_mfma_f32_16x16x32_bf16 v[76:79], v[182:185], v[204:207], v[76:79]
	v_mfma_f32_16x16x32_bf16 v[72:75], v[182:185], v[212:215], v[72:75]
	v_mfma_f32_16x16x32_bf16 v[68:71], v[196:199], v[204:207], v[68:71]
	v_mfma_f32_16x16x32_bf16 v[64:67], v[196:199], v[212:215], v[64:67]
	s_add_u32 s54, s75, 0x180
	s_addc_u32 s55, s78, 0
	s_add_i32 m0, s14, 0x8000
	s_barrier
	ds_read_b128 v[162:165], v195 offset:49152
	ds_read_b128 v[166:169], v195 offset:50176
	ds_read_b128 v[170:173], v195 offset:51200
	ds_read_b128 v[174:177], v195 offset:52224
	ds_read_b128 v[178:181], v195 offset:53248
	ds_read_b128 v[182:185], v195 offset:54272
	ds_read_b128 v[186:189], v195 offset:55296
	ds_read_b128 v[196:199], v195 offset:56320
	global_load_lds_dwordx4 v192, s[54:55]
	s_add_u32 s10, s54, s34
	s_addc_u32 s11, s55, s35
	s_add_i32 m0, s14, 0xa000
	s_nop 0
	global_load_lds_dwordx4 v192, s[10:11]
	s_barrier
	s_waitcnt lgkmcnt(0)
	s_waitcnt lgkmcnt(0)
	v_mfma_f32_16x16x32_bf16 v[60:63], v[162:165], v[146:149], v[60:63]
	v_mfma_f32_16x16x32_bf16 v[56:59], v[162:165], v[154:157], v[56:59]
	v_mfma_f32_16x16x32_bf16 v[52:55], v[170:173], v[146:149], v[52:55]
	v_mfma_f32_16x16x32_bf16 v[48:51], v[170:173], v[154:157], v[48:51]
	v_mfma_f32_16x16x32_bf16 v[44:47], v[178:181], v[146:149], v[44:47]
	v_mfma_f32_16x16x32_bf16 v[40:43], v[178:181], v[154:157], v[40:43]
	v_mfma_f32_16x16x32_bf16 v[36:39], v[186:189], v[146:149], v[36:39]
	v_mfma_f32_16x16x32_bf16 v[32:35], v[186:189], v[154:157], v[32:35]
	v_mfma_f32_16x16x32_bf16 v[60:63], v[166:169], v[150:153], v[60:63]
	v_mfma_f32_16x16x32_bf16 v[56:59], v[166:169], v[158:161], v[56:59]
	v_mfma_f32_16x16x32_bf16 v[52:55], v[174:177], v[150:153], v[52:55]
	v_mfma_f32_16x16x32_bf16 v[48:51], v[174:177], v[158:161], v[48:51]
	v_mfma_f32_16x16x32_bf16 v[44:47], v[182:185], v[150:153], v[44:47]
	v_mfma_f32_16x16x32_bf16 v[40:43], v[182:185], v[158:161], v[40:43]
	v_mfma_f32_16x16x32_bf16 v[36:39], v[196:199], v[150:153], v[36:39]
	v_mfma_f32_16x16x32_bf16 v[32:35], v[196:199], v[158:161], v[32:35]
	s_barrier
	s_add_u32 s54, s79, 0x180
	s_addc_u32 s55, s80, 0
	s_add_i32 m0, s14, s89
	s_nop 0
	global_load_lds_dwordx4 v192, s[54:55]
	s_add_u32 s10, s54, s34
	s_addc_u32 s11, s55, s35
	s_add_i32 m0, s14, s89
	s_add_i32 m0, m0, 0x2000
	s_nop 0
	global_load_lds_dwordx4 v192, s[10:11]
	s_waitcnt vmcnt(6)
	s_barrier
	v_mfma_f32_16x16x32_bf16 v[28:31], v[162:165], v[200:203], v[28:31]
	v_mfma_f32_16x16x32_bf16 v[24:27], v[162:165], v[208:211], v[24:27]
	v_mfma_f32_16x16x32_bf16 v[20:23], v[170:173], v[200:203], v[20:23]
	v_mfma_f32_16x16x32_bf16 v[16:19], v[170:173], v[208:211], v[16:19]
	v_mfma_f32_16x16x32_bf16 v[12:15], v[178:181], v[200:203], v[12:15]
	v_mfma_f32_16x16x32_bf16 v[8:11], v[178:181], v[208:211], v[8:11]
	v_mfma_f32_16x16x32_bf16 v[4:7], v[186:189], v[200:203], v[4:7]
	v_mfma_f32_16x16x32_bf16 v[0:3], v[186:189], v[208:211], v[0:3]
	v_mfma_f32_16x16x32_bf16 v[28:31], v[166:169], v[204:207], v[28:31]
	v_mfma_f32_16x16x32_bf16 v[24:27], v[166:169], v[212:215], v[24:27]
	v_mfma_f32_16x16x32_bf16 v[20:23], v[174:177], v[204:207], v[20:23]
	v_mfma_f32_16x16x32_bf16 v[16:19], v[174:177], v[212:215], v[16:19]
	v_mfma_f32_16x16x32_bf16 v[12:15], v[182:185], v[204:207], v[12:15]
	v_mfma_f32_16x16x32_bf16 v[8:11], v[182:185], v[212:215], v[8:11]
	v_mfma_f32_16x16x32_bf16 v[4:7], v[196:199], v[204:207], v[4:7]
	v_mfma_f32_16x16x32_bf16 v[0:3], v[196:199], v[212:215], v[0:3]
	s_add_i32 s3, s3, 2
	s_add_u32 s48, s48, 0x100
	s_addc_u32 s49, s49, 0
	s_cmp_lt_u32 s3, 12
	s_barrier
	s_cbranch_scc1 .LBB0_1020
	v_add_u32_e32 v190, 0, v136
	s_add_u32 s38, s46, 0x780
	v_add_u32_e32 v140, 0x10000, v190
	s_addc_u32 s39, s47, 0
	v_readfirstlane_b32 s3, v143
	ds_read_b128 v[128:131], v140
	ds_read_b128 v[132:135], v140 offset:1024
	ds_read_b128 v[136:139], v140 offset:2048
	ds_read_b128 v[146:149], v140 offset:3072
	ds_read_b128 v[150:153], v195
	ds_read_b128 v[154:157], v195 offset:1024
	ds_read_b128 v[158:161], v195 offset:2048
	ds_read_b128 v[162:165], v195 offset:3072
	ds_read_b128 v[166:169], v195 offset:4096
	ds_read_b128 v[170:173], v195 offset:5120
	ds_read_b128 v[174:177], v195 offset:6144
	ds_read_b128 v[178:181], v195 offset:7168
	v_lshl_add_u64 v[140:141], s[38:39], 0, v[192:193]
	s_mov_b32 m0, s3
	v_readfirstlane_b32 s3, v144
	global_load_lds_dwordx4 v[140:141], off
	v_lshl_add_u64 v[140:141], v[140:141], 0, s[34:35]
	s_mov_b32 m0, s3
	s_nop 0
	global_load_lds_dwordx4 v[140:141], off
	s_barrier
	s_waitcnt lgkmcnt(0)
	s_waitcnt lgkmcnt(0)
	v_mfma_f32_16x16x32_bf16 v[124:127], v[150:153], v[128:131], v[124:127]
	v_mfma_f32_16x16x32_bf16 v[120:123], v[150:153], v[136:139], v[120:123]
	v_mfma_f32_16x16x32_bf16 v[116:119], v[158:161], v[128:131], v[116:119]
	v_mfma_f32_16x16x32_bf16 v[112:115], v[158:161], v[136:139], v[112:115]
	v_mfma_f32_16x16x32_bf16 v[108:111], v[166:169], v[128:131], v[108:111]
	v_mfma_f32_16x16x32_bf16 v[104:107], v[166:169], v[136:139], v[104:107]
	v_mfma_f32_16x16x32_bf16 v[100:103], v[174:177], v[128:131], v[100:103]
	v_mfma_f32_16x16x32_bf16 v[96:99], v[174:177], v[136:139], v[96:99]
	v_mfma_f32_16x16x32_bf16 v[124:127], v[154:157], v[132:135], v[124:127]
	v_mfma_f32_16x16x32_bf16 v[120:123], v[154:157], v[146:149], v[120:123]
	v_mfma_f32_16x16x32_bf16 v[116:119], v[162:165], v[132:135], v[116:119]
	v_mfma_f32_16x16x32_bf16 v[112:115], v[162:165], v[146:149], v[112:115]
	v_mfma_f32_16x16x32_bf16 v[108:111], v[170:173], v[132:135], v[108:111]
	v_mfma_f32_16x16x32_bf16 v[104:107], v[170:173], v[146:149], v[104:107]
	v_mfma_f32_16x16x32_bf16 v[100:103], v[178:181], v[132:135], v[100:103]
	v_mfma_f32_16x16x32_bf16 v[96:99], v[178:181], v[146:149], v[96:99]
	v_add_u32_e32 v144, 0x14000, v190
	s_barrier
	ds_read_b128 v[140:143], v144
	ds_read_b128 v[182:185], v144 offset:1024
	ds_read_b128 v[186:189], v144 offset:2048
	ds_read_b128 v[196:199], v144 offset:3072
	s_barrier
	s_waitcnt lgkmcnt(0)
	s_waitcnt lgkmcnt(0)
	v_mfma_f32_16x16x32_bf16 v[92:95], v[150:153], v[140:143], v[92:95]
	v_mfma_f32_16x16x32_bf16 v[88:91], v[150:153], v[186:189], v[88:91]
	v_mfma_f32_16x16x32_bf16 v[84:87], v[158:161], v[140:143], v[84:87]
	v_mfma_f32_16x16x32_bf16 v[80:83], v[158:161], v[186:189], v[80:83]
	v_mfma_f32_16x16x32_bf16 v[76:79], v[166:169], v[140:143], v[76:79]
	v_mfma_f32_16x16x32_bf16 v[72:75], v[166:169], v[186:189], v[72:75]
	v_mfma_f32_16x16x32_bf16 v[68:71], v[174:177], v[140:143], v[68:71]
	v_mfma_f32_16x16x32_bf16 v[64:67], v[174:177], v[186:189], v[64:67]
	v_mfma_f32_16x16x32_bf16 v[92:95], v[154:157], v[182:185], v[92:95]
	v_mfma_f32_16x16x32_bf16 v[88:91], v[154:157], v[196:199], v[88:91]
	v_mfma_f32_16x16x32_bf16 v[84:87], v[162:165], v[182:185], v[84:87]
	v_mfma_f32_16x16x32_bf16 v[80:83], v[162:165], v[196:199], v[80:83]
	v_mfma_f32_16x16x32_bf16 v[76:79], v[170:173], v[182:185], v[76:79]
	v_mfma_f32_16x16x32_bf16 v[72:75], v[170:173], v[196:199], v[72:75]
	v_mfma_f32_16x16x32_bf16 v[68:71], v[178:181], v[182:185], v[68:71]
	v_mfma_f32_16x16x32_bf16 v[64:67], v[178:181], v[196:199], v[64:67]
	s_barrier
	ds_read_b128 v[150:153], v195 offset:16384
	ds_read_b128 v[154:157], v195 offset:17408
	ds_read_b128 v[158:161], v195 offset:18432
	ds_read_b128 v[162:165], v195 offset:19456
	ds_read_b128 v[166:169], v195 offset:20480
	ds_read_b128 v[170:173], v195 offset:21504
	ds_read_b128 v[174:177], v195 offset:22528
	ds_read_b128 v[178:181], v195 offset:23552
	s_waitcnt vmcnt(4)
	s_barrier
	s_waitcnt lgkmcnt(0)
	s_waitcnt lgkmcnt(0)
	v_mfma_f32_16x16x32_bf16 v[60:63], v[150:153], v[128:131], v[60:63]
	v_mfma_f32_16x16x32_bf16 v[56:59], v[150:153], v[136:139], v[56:59]
	v_mfma_f32_16x16x32_bf16 v[52:55], v[158:161], v[128:131], v[52:55]
	v_mfma_f32_16x16x32_bf16 v[48:51], v[158:161], v[136:139], v[48:51]
	v_mfma_f32_16x16x32_bf16 v[44:47], v[166:169], v[128:131], v[44:47]
	v_mfma_f32_16x16x32_bf16 v[40:43], v[166:169], v[136:139], v[40:43]
	v_mfma_f32_16x16x32_bf16 v[36:39], v[174:177], v[128:131], v[36:39]
	v_mfma_f32_16x16x32_bf16 v[32:35], v[174:177], v[136:139], v[32:35]
	v_mfma_f32_16x16x32_bf16 v[60:63], v[154:157], v[132:135], v[60:63]
	v_mfma_f32_16x16x32_bf16 v[56:59], v[154:157], v[146:149], v[56:59]
	v_mfma_f32_16x16x32_bf16 v[52:55], v[162:165], v[132:135], v[52:55]
	v_mfma_f32_16x16x32_bf16 v[48:51], v[162:165], v[146:149], v[48:51]
	v_mfma_f32_16x16x32_bf16 v[44:47], v[170:173], v[132:135], v[44:47]
	v_mfma_f32_16x16x32_bf16 v[40:43], v[170:173], v[146:149], v[40:43]
	v_mfma_f32_16x16x32_bf16 v[36:39], v[178:181], v[132:135], v[36:39]
	v_mfma_f32_16x16x32_bf16 v[32:35], v[178:181], v[146:149], v[32:35]
	v_mfma_f32_16x16x32_bf16 v[28:31], v[150:153], v[140:143], v[28:31]
	v_mfma_f32_16x16x32_bf16 v[24:27], v[150:153], v[186:189], v[24:27]
	v_mfma_f32_16x16x32_bf16 v[20:23], v[158:161], v[140:143], v[20:23]
	v_mfma_f32_16x16x32_bf16 v[16:19], v[158:161], v[186:189], v[16:19]
	v_mfma_f32_16x16x32_bf16 v[12:15], v[166:169], v[140:143], v[12:15]
	v_mfma_f32_16x16x32_bf16 v[8:11], v[166:169], v[186:189], v[8:11]
	v_mfma_f32_16x16x32_bf16 v[4:7], v[174:177], v[140:143], v[4:7]
	v_mfma_f32_16x16x32_bf16 v[0:3], v[174:177], v[186:189], v[0:3]
	v_mfma_f32_16x16x32_bf16 v[200:203], v[154:157], v[182:185], v[28:31]
	v_mfma_f32_16x16x32_bf16 v[204:207], v[154:157], v[196:199], v[24:27]
	v_mfma_f32_16x16x32_bf16 v[208:211], v[162:165], v[182:185], v[20:23]
	v_mfma_f32_16x16x32_bf16 v[212:215], v[162:165], v[196:199], v[16:19]
	v_mfma_f32_16x16x32_bf16 v[216:219], v[170:173], v[182:185], v[12:15]
	v_mfma_f32_16x16x32_bf16 v[220:223], v[170:173], v[196:199], v[8:11]
	v_mfma_f32_16x16x32_bf16 v[224:227], v[178:181], v[182:185], v[4:7]
	v_mfma_f32_16x16x32_bf16 v[196:199], v[178:181], v[196:199], v[0:3]
	s_nop 1
	v_add_u32_e32 v0, 0x18000, v190
	s_barrier
	ds_read_b128 v[24:27], v0
	ds_read_b128 v[28:31], v0 offset:1024
	ds_read_b128 v[228:231], v0 offset:2048
	ds_read_b128 v[240:243], v0 offset:3072
	ds_read_b128 v[0:3], v195 offset:32768
	ds_read_b128 v[4:7], v195 offset:33792
	ds_read_b128 v[8:11], v195 offset:34816
	ds_read_b128 v[12:15], v195 offset:35840
	ds_read_b128 v[16:19], v195 offset:36864
	ds_read_b128 v[20:23], v195 offset:37888
	ds_read_b128 v[184:187], v195 offset:38912
	ds_read_b128 v[248:251], v195 offset:39936
	s_waitcnt vmcnt(2)
	s_barrier
	s_waitcnt lgkmcnt(0)
	s_waitcnt lgkmcnt(0)
	v_mfma_f32_16x16x32_bf16 v[124:127], v[0:3], v[24:27], v[124:127]
	v_mfma_f32_16x16x32_bf16 v[120:123], v[0:3], v[228:231], v[120:123]
	v_mfma_f32_16x16x32_bf16 v[116:119], v[8:11], v[24:27], v[116:119]
	v_mfma_f32_16x16x32_bf16 v[112:115], v[8:11], v[228:231], v[112:115]
	v_mfma_f32_16x16x32_bf16 v[108:111], v[16:19], v[24:27], v[108:111]
	v_mfma_f32_16x16x32_bf16 v[104:107], v[16:19], v[228:231], v[104:107]
	v_mfma_f32_16x16x32_bf16 v[100:103], v[184:187], v[24:27], v[100:103]
	v_mfma_f32_16x16x32_bf16 v[96:99], v[184:187], v[228:231], v[96:99]
	v_mfma_f32_16x16x32_bf16 v[156:159], v[4:7], v[28:31], v[124:127]
	v_mfma_f32_16x16x32_bf16 v[128:131], v[4:7], v[240:243], v[120:123]
	v_mfma_f32_16x16x32_bf16 v[132:135], v[12:15], v[28:31], v[116:119]
	v_mfma_f32_16x16x32_bf16 v[136:139], v[12:15], v[240:243], v[112:115]
	v_mfma_f32_16x16x32_bf16 v[140:143], v[20:23], v[28:31], v[108:111]
	v_mfma_f32_16x16x32_bf16 v[144:147], v[20:23], v[240:243], v[104:107]
	v_mfma_f32_16x16x32_bf16 v[148:151], v[248:251], v[28:31], v[100:103]
	v_mfma_f32_16x16x32_bf16 v[152:155], v[248:251], v[240:243], v[96:99]
	v_add_u32_e32 v108, 0x1c000, v190
	s_barrier
	ds_read_b128 v[96:99], v108
	ds_read_b128 v[100:103], v108 offset:1024
	ds_read_b128 v[104:107], v108 offset:2048
	ds_read_b128 v[108:111], v108 offset:3072
	s_waitcnt vmcnt(0)
	s_barrier
	s_waitcnt lgkmcnt(0)
	s_waitcnt lgkmcnt(0)
	v_mfma_f32_16x16x32_bf16 v[92:95], v[0:3], v[96:99], v[92:95]
	v_mfma_f32_16x16x32_bf16 v[0:3], v[0:3], v[104:107], v[88:91]
	v_mfma_f32_16x16x32_bf16 v[160:163], v[4:7], v[108:111], v[0:3]
	v_mfma_f32_16x16x32_bf16 v[0:3], v[8:11], v[96:99], v[84:87]
	v_mfma_f32_16x16x32_bf16 v[164:167], v[12:15], v[100:103], v[0:3]
	v_mfma_f32_16x16x32_bf16 v[0:3], v[8:11], v[104:107], v[80:83]
	v_mfma_f32_16x16x32_bf16 v[168:171], v[12:15], v[108:111], v[0:3]
	v_mfma_f32_16x16x32_bf16 v[0:3], v[16:19], v[96:99], v[76:79]
	v_mfma_f32_16x16x32_bf16 v[172:175], v[20:23], v[100:103], v[0:3]
	v_mfma_f32_16x16x32_bf16 v[0:3], v[16:19], v[104:107], v[72:75]
	v_mfma_f32_16x16x32_bf16 v[176:179], v[20:23], v[108:111], v[0:3]
	v_mfma_f32_16x16x32_bf16 v[0:3], v[184:187], v[96:99], v[68:71]
	v_mfma_f32_16x16x32_bf16 v[180:183], v[248:251], v[100:103], v[0:3]
	v_mfma_f32_16x16x32_bf16 v[0:3], v[184:187], v[104:107], v[64:67]
	v_mfma_f32_16x16x32_bf16 v[188:191], v[4:7], v[100:103], v[92:95]
	v_mfma_f32_16x16x32_bf16 v[184:187], v[248:251], v[108:111], v[0:3]
	s_barrier
	ds_read_b128 v[64:67], v195 offset:49152
	ds_read_b128 v[68:71], v195 offset:50176
	ds_read_b128 v[72:75], v195 offset:51200
	ds_read_b128 v[76:79], v195 offset:52224
	ds_read_b128 v[80:83], v195 offset:53248
	ds_read_b128 v[84:87], v195 offset:54272
	ds_read_b128 v[88:91], v195 offset:55296
	ds_read_b128 v[92:95], v195 offset:56320
	s_barrier
	s_waitcnt lgkmcnt(0)
	s_waitcnt lgkmcnt(0)
	v_mfma_f32_16x16x32_bf16 v[0:3], v[64:67], v[24:27], v[60:63]
	v_mfma_f32_16x16x32_bf16 v[8:11], v[72:75], v[24:27], v[52:55]
	v_mfma_f32_16x16x32_bf16 v[16:19], v[80:83], v[24:27], v[44:47]
	v_mfma_f32_16x16x32_bf16 v[24:27], v[88:91], v[24:27], v[36:39]
	v_mfma_f32_16x16x32_bf16 v[0:3], v[68:71], v[28:31], v[0:3]
	v_mfma_f32_16x16x32_bf16 v[4:7], v[64:67], v[228:231], v[56:59]
	v_mfma_f32_16x16x32_bf16 v[8:11], v[76:79], v[28:31], v[8:11]
	v_mfma_f32_16x16x32_bf16 v[12:15], v[72:75], v[228:231], v[48:51]
	v_mfma_f32_16x16x32_bf16 v[16:19], v[84:87], v[28:31], v[16:19]
	v_mfma_f32_16x16x32_bf16 v[20:23], v[80:83], v[228:231], v[40:43]
	v_mfma_f32_16x16x32_bf16 v[24:27], v[92:95], v[28:31], v[24:27]
	v_mfma_f32_16x16x32_bf16 v[28:31], v[88:91], v[228:231], v[32:35]
	v_mfma_f32_16x16x32_bf16 v[4:7], v[68:71], v[240:243], v[4:7]
	v_mfma_f32_16x16x32_bf16 v[12:15], v[76:79], v[240:243], v[12:15]
	v_mfma_f32_16x16x32_bf16 v[20:23], v[84:87], v[240:243], v[20:23]
	v_mfma_f32_16x16x32_bf16 v[28:31], v[92:95], v[240:243], v[28:31]
	v_mfma_f32_16x16x32_bf16 v[32:35], v[64:67], v[96:99], v[200:203]
	v_mfma_f32_16x16x32_bf16 v[36:39], v[64:67], v[104:107], v[204:207]
	v_mfma_f32_16x16x32_bf16 v[40:43], v[72:75], v[96:99], v[208:211]
	v_mfma_f32_16x16x32_bf16 v[44:47], v[72:75], v[104:107], v[212:215]
	v_mfma_f32_16x16x32_bf16 v[48:51], v[80:83], v[96:99], v[216:219]
	v_mfma_f32_16x16x32_bf16 v[52:55], v[80:83], v[104:107], v[220:223]
	v_mfma_f32_16x16x32_bf16 v[56:59], v[88:91], v[96:99], v[224:227]
	v_mfma_f32_16x16x32_bf16 v[60:63], v[88:91], v[104:107], v[196:199]
	v_mfma_f32_16x16x32_bf16 v[32:35], v[68:71], v[100:103], v[32:35]
	v_mfma_f32_16x16x32_bf16 v[36:39], v[68:71], v[108:111], v[36:39]
	v_mfma_f32_16x16x32_bf16 v[40:43], v[76:79], v[100:103], v[40:43]
	v_mfma_f32_16x16x32_bf16 v[44:47], v[76:79], v[108:111], v[44:47]
	v_mfma_f32_16x16x32_bf16 v[48:51], v[84:87], v[100:103], v[48:51]
	v_mfma_f32_16x16x32_bf16 v[52:55], v[84:87], v[108:111], v[52:55]
	v_mfma_f32_16x16x32_bf16 v[56:59], v[92:95], v[100:103], v[56:59]
	v_mfma_f32_16x16x32_bf16 v[60:63], v[92:95], v[108:111], v[60:63]
	s_cmpk_gt_u32 s53, 0xff
	s_barrier
	s_cbranch_scc1 .LBB0_1023
	s_barrier
